# attention loop: intra-tile pipelining (QK of keys 32-63 overlaps exp of keys 0-31, PV 1-4 overlaps exp of keys 32-63); fused-LN residual loads as rolling prefetch; P5 gate loads hoisted; no store drai
# speedup vs baseline: 1.0487x; 1.0056x over previous
.LBB0_759:
	s_waitcnt vmcnt(0)
	v_lshlrev_b32_e32 v12, 16, v14
	s_and_b32 s30, s57, 0x3fffffc0
	v_lshlrev_b32_e32 v10, 16, v18
	v_pk_mul_f32 v[12:13], v[4:5], v[12:13] op_sel:[1,0] op_sel_hi:[0,0]
	s_lshl_b32 s30, s30, 2
	v_pk_fma_f32 v[30:31], v[4:5], v[10:11], v[12:13] neg_lo:[0,0,1] neg_hi:[0,0,1]
	v_pk_fma_f32 v[4:5], v[4:5], v[10:11], v[12:13] op_sel_hi:[1,0,1]
	v_and_b32_e32 v10, 0xffff0000, v14
	s_add_i32 s30, s30, 0
	v_and_b32_e32 v4, 0xffff0000, v18
	v_pk_mul_f32 v[10:11], v[6:7], v[10:11] op_sel:[1,0] op_sel_hi:[0,0]
	v_mov_b32_e32 v9, v137
	s_add_i32 s30, s30, 0x14000
	v_cvt_pk_bf16_f32 v38, v30, v5
	v_pk_fma_f32 v[12:13], v[6:7], v[4:5], v[10:11] neg_lo:[0,0,1] neg_hi:[0,0,1]
	v_pk_fma_f32 v[4:5], v[6:7], v[4:5], v[10:11] op_sel_hi:[1,0,1]
	v_lshlrev_b32_e32 v6, 16, v15
	v_lshl_add_u64 v[154:155], s[6:7], 0, v[8:9]
	s_or_b32 s6, s34, 0x10000
	v_lshlrev_b32_e32 v4, 16, v19
	v_pk_mul_f32 v[6:7], v[0:1], v[6:7] op_sel:[1,0] op_sel_hi:[0,0]
	s_mov_b32 s7, s11
	s_cmp_lg_u32 0, -1
	v_cvt_pk_bf16_f32 v39, v12, v5
	v_pk_fma_f32 v[10:11], v[0:1], v[4:5], v[6:7] neg_lo:[0,0,1] neg_hi:[0,0,1]
	v_pk_fma_f32 v[0:1], v[0:1], v[4:5], v[6:7] op_sel_hi:[1,0,1]
	v_lshl_add_u64 v[4:5], v[154:155], 0, s[6:7]
	s_cselect_b32 s6, 0, 0
	s_add_i32 s6, s6, s55
	s_add_i32 s6, s6, 0x10000
	s_mov_b32 s7, m0
	s_mov_b32 m0, s6
	s_nop 0
	global_load_lds_dwordx4 v[4:5], off
	s_mov_b32 m0, s7
	ds_read_b128 v[4:7], v151
	ds_read_b128 v[30:33], v151 offset:2048
	v_cvt_pk_bf16_f32 v40, v10, v1
	v_and_b32_e32 v10, 0xffff0000, v15
	v_and_b32_e32 v0, 0xffff0000, v19
	v_pk_mul_f32 v[8:9], v[2:3], v[10:11] op_sel:[1,0] op_sel_hi:[0,0]
	v_pk_fma_f32 v[10:11], v[2:3], v[0:1], v[8:9] neg_lo:[0,0,1] neg_hi:[0,0,1]
	v_pk_fma_f32 v[0:1], v[2:3], v[0:1], v[8:9] op_sel_hi:[1,0,1]
	v_lshlrev_b32_e32 v34, 16, v16
	v_cvt_pk_bf16_f32 v41, v10, v1
	s_waitcnt lgkmcnt(1)
	v_mfma_f32_32x32x16_bf16 v[0:15], v[4:7], v[92:95], 0
	v_lshlrev_b32_e32 v18, 16, v20
	v_pk_mul_f32 v[34:35], v[26:27], v[34:35] op_sel:[1,0] op_sel_hi:[0,0]
	v_pk_fma_f32 v[36:37], v[26:27], v[18:19], v[34:35] neg_lo:[0,0,1] neg_hi:[0,0,1]
	v_pk_fma_f32 v[18:19], v[26:27], v[18:19], v[34:35] op_sel_hi:[1,0,1]
	v_and_b32_e32 v16, 0xffff0000, v16
	v_cvt_pk_bf16_f32 v42, v36, v19
	ds_read_b128 v[34:37], v151 offset:4096
	s_waitcnt lgkmcnt(1)
	v_mfma_f32_32x32x16_bf16 v[0:15], v[30:33], v[88:91], v[0:15]
	v_and_b32_e32 v18, 0xffff0000, v20
	v_mul_f32_e64 v26, v29, v16
	v_mul_f32_e64 v27, v28, v16
	v_fma_f32 v30, v28, v18, -v26
	v_fma_f32 v31, v29, v19, -v27
	v_pk_fma_f32 v[18:19], v[28:29], v[18:19], v[26:27] op_sel_hi:[1,0,1]
	ds_read_b128 v[26:29], v151 offset:6144
	v_lshlrev_b32_e32 v18, 16, v17
	v_cvt_pk_bf16_f32 v32, v30, v19
	s_waitcnt lgkmcnt(1)
	v_mfma_f32_32x32x16_bf16 v[0:15], v[34:37], v[84:87], v[0:15]
	v_lshlrev_b32_e32 v16, 16, v21
	v_pk_mul_f32 v[18:19], v[22:23], v[18:19] op_sel:[1,0] op_sel_hi:[0,0]
	v_pk_fma_f32 v[30:31], v[22:23], v[16:17], v[18:19] neg_lo:[0,0,1] neg_hi:[0,0,1]
	v_pk_fma_f32 v[18:19], v[22:23], v[16:17], v[18:19] op_sel_hi:[1,0,1]
	v_and_b32_e32 v16, 0xffff0000, v21
	v_cvt_pk_bf16_f32 v30, v30, v19
	ds_read_b128 v[18:21], v151 offset:8192
	s_waitcnt lgkmcnt(1)
	v_mfma_f32_32x32x16_bf16 v[0:15], v[26:29], v[80:83], v[0:15]
	v_and_b32_e32 v22, 0xffff0000, v17
	v_pk_mul_f32 v[22:23], v[24:25], v[22:23] op_sel:[1,0] op_sel_hi:[0,0]
	v_pk_fma_f32 v[26:27], v[24:25], v[16:17], v[22:23] neg_lo:[0,0,1] neg_hi:[0,0,1]
	v_pk_fma_f32 v[16:17], v[24:25], v[16:17], v[22:23] op_sel_hi:[1,0,1]
	v_perm_b32 v96, v39, v38, s48
	v_cvt_pk_bf16_f32 v16, v26, v17
	v_perm_b32 v97, v41, v40, s48
	v_perm_b32 v98, v32, v42, s48
	v_perm_b32 v99, v16, v30, s48
	ds_read_b128 v[22:25], v151 offset:10240
	v_perm_b32 v101, v41, v40, s49
	s_waitcnt lgkmcnt(1)
	v_mfma_f32_32x32x16_bf16 v[0:15], v[18:21], v[96:99], v[0:15]
	ds_read_b64_tr_b16 v[40:41],v161 offset:0
	v_perm_b32 v102, v32, v42, s49
	ds_read_b64_tr_b16 v[42:43],v161 offset:512
	ds_read_b64_tr_b16 v[44:45],v161 offset:1024
	ds_read_b64_tr_b16 v[46:47],v161 offset:1536
	ds_read_b64_tr_b16 v[68:69],v161 offset:2048
	ds_read_b64_tr_b16 v[70:71],v161 offset:2560
	ds_read_b64_tr_b16 v[64:65],v161 offset:3072
	v_perm_b32 v100, v39, v38, s49
	v_perm_b32 v103, v16, v30, s49
	ds_read_b64_tr_b16 v[66:67],v161 offset:3584
	ds_read_b64_tr_b16 v[60:61],v161 offset:4096
	ds_read_b64_tr_b16 v[62:63],v161 offset:4608
	ds_read_b64_tr_b16 v[56:57],v161 offset:5120
	ds_read_b64_tr_b16 v[58:59],v161 offset:5632
	s_waitcnt lgkmcnt(0)
	s_nop 0
	v_mfma_f32_32x32x16_bf16 v[0:15], v[22:25], v[100:103], v[0:15]
	v_max3_f32 v8, v0, v1, v168
	v_max3_f32 v9, v2, v3, v168
	ds_read_b64_tr_b16 v[52:53],v161 offset:6144
	ds_read_b64_tr_b16 v[54:55],v161 offset:6656
	ds_read_b64_tr_b16 v[48:49],v161 offset:7168
	ds_read_b64_tr_b16 v[50:51],v161 offset:7680
	s_nop 0
	v_max3_f32 v8, v8, v168, v168
	v_max3_f32 v9, v9, v6, v7
	v_lshl_add_u32 v171, v143, 2, s30
	v_max3_f32 v8, v8, v4, v5
	v_max3_f32 v9, v9, v168, v168
	s_nop 0
	v_max3_f32 v8, v8, v168, v168
	v_max3_f32 v9, v9, v168, v168
	s_nop 0
	v_max3_f32 v8, v8, v168, v168
	v_max3_f32 v9, v9, v168, v168
	s_nop 0
	v_max3_f32 v8, v8, v168, v168
	v_max3_f32 v9, v9, v168, v168
	s_nop 0
	v_max3_f32 v8, v8, v168, v168
	v_max3_f32 v9, v9, v168, v168
	s_nop 0
	v_max3_f32 v8, v8, v168, v168
	s_nop 0
	v_max_f32_e32 v8, v8, v9
	s_nop 3
	v_mov_b32_e32 v9, v8
	s_nop 1
	v_permlane32_swap_b32_e32 v8, v9
	v_max_f32_e32 v174, v8, v9
	s_and_saveexec_b64 s[6:7], s[0:1]
	ds_write_b32 v171, v137
	s_or_b64 exec, exec, s[6:7]
	s_waitcnt lgkmcnt(0)
	v_add_u32_e32 v172, s30, v162
	v_sub_f32_e32 v24, v0, v174
	v_sub_f32_e32 v26, v1, v174
	v_sub_f32_e32 v27, v2, v174
	v_sub_f32_e32 v28, v3, v174
	v_sub_f32_e32 v29, v4, v174
	v_sub_f32_e32 v30, v5, v174
	v_sub_f32_e32 v31, v6, v174
	v_sub_f32_e32 v39, v7, v174
	ds_read_b128 v[0:3], v172 offset:64
	ds_read_b128 v[4:7], v172 offset:96
	ds_read_b128 v[16:19], v172
	ds_read_b128 v[20:23], v172 offset:32
	v_sub_f32_e32 v25, 0xf149f2ca, v174
	s_waitcnt lgkmcnt(3)
	v_pk_mul_f32 v[8:9], v[0:1], 0 op_sel_hi:[1,0]
	v_exp_f32_e32 v104, v25
	s_waitcnt lgkmcnt(1)
	v_pk_mul_f32 v[0:1], v[16:17], 0 op_sel_hi:[1,0]
	v_exp_f32_e32 v17, v30
	v_exp_f32_e32 v16, v31
	v_exp_f32_e32 v108, v24
	v_exp_f32_e32 v109, v26
	v_exp_f32_e32 v110, v27
	v_exp_f32_e32 v111, v28
	v_exp_f32_e32 v112, v29
	v_pk_add_f32 v[106:107], v[16:17], v[104:105] op_sel_hi:[1,0]
	v_exp_f32_e32 v105, v39
	v_cvt_pk_bf16_f32 v72, v108, v109
	v_cvt_pk_bf16_f32 v73, v110, v111
	v_cvt_pk_bf16_f32 v74, v112, v17
	v_cvt_pk_bf16_f32 v75, v16, v105
	v_pk_mul_f32 v[14:15], v[6:7], 0 op_sel_hi:[1,0]
	v_pk_mul_f32 v[10:11], v[2:3], 0 op_sel_hi:[1,0]
	s_waitcnt lgkmcnt(0)
	v_pk_mul_f32 v[6:7], v[22:23], 0 op_sel_hi:[1,0]
	v_pk_mul_f32 v[2:3], v[18:19], 0 op_sel_hi:[1,0]
	v_pk_mul_f32 v[12:13], v[4:5], 0 op_sel_hi:[1,0]
	v_pk_mul_f32 v[4:5], v[20:21], 0 op_sel_hi:[1,0]
	s_waitcnt lgkmcnt(0)
	v_cvt_pk_bf16_f32 v76, v104, v104
	v_mov_b32_e32 v77, v76
	v_mfma_f32_32x32x16_bf16 v[16:31], v[72:75], v[40:43], v[0:15]
	v_mov_b32_e32 v78, v76
	v_mov_b32_e32 v79, v76
	s_lshl_b32 s30, s36, 2
	s_or_b32 s31, s30, 2
	s_lshr_b32 s6, s57, 7
	s_lshl_b32 s54, s37, 6
	s_add_i32 s57, s31, s6
	v_mfma_f32_32x32x16_bf16 v[16:31], v[76:79], v[44:47], v[16:31]
	s_add_i32 s59, s55, 0x2000
	s_cmp_lg_u32 0, -1
	s_cselect_b32 s6, 0, 0
	s_add_i32 s58, s6, s55
	s_bfe_u32 s34, s44, 0x3000c
	s_lshl_b32 s6, s44, 10
	s_and_b32 s6, s6, 0x1c00000
	v_mfma_f32_32x32x16_bf16 v[0:15], v[72:75], v[60:63], v[0:15]
	v_add_f32_e32 v61, v109, v104
	s_mov_b32 s7, s11
	s_mul_i32 s34, s34, 0x600000
	s_mulk_i32 s37, 0xc0
	s_add_i32 s58, s58, 0xc000
	v_xor_b32_e32 v32, 0x80000000, v174
	v_mov_b32_e32 v33, v32
	v_mfma_f32_32x32x16_bf16 v[16:31], v[76:79], v[68:71], v[16:31]
	v_mov_b32_e32 v34, v32
	v_mov_b32_e32 v35, v32
	v_mov_b32_e32 v36, v32
	v_mov_b32_e32 v37, v32
	v_mov_b32_e32 v38, v32
	v_mov_b32_e32 v39, v32
	v_mov_b32_e32 v40, v32
	v_mfma_f32_32x32x16_bf16 v[0:15], v[76:79], v[56:59], v[0:15]
	v_add_f32_e32 v56, v112, v104
	v_mov_b32_e32 v41, v32
	v_mov_b32_e32 v42, v32
	v_mov_b32_e32 v43, v32
	v_mov_b32_e32 v44, v32
	v_mov_b32_e32 v45, v32
	v_mov_b32_e32 v46, v32
	v_mfma_f32_32x32x16_bf16 v[16:31], v[76:79], v[64:67], v[16:31]
	v_add_f32_e32 v64, v108, v104
	v_add_f32_e32 v60, 0, v64
	v_add_f32_e32 v60, v61, v60
	v_add_f32_e32 v61, v110, v104
	v_add_f32_e32 v60, v61, v60
	v_add_f32_e32 v61, v111, v104
	v_add_f32_e32 v60, v61, v60
	v_mfma_f32_32x32x16_bf16 v[0:15], v[76:79], v[52:55], v[0:15]
	v_add_f32_e32 v56, v56, v60
	v_add_f32_e32 v56, v107, v56
	v_add_f32_e32 v58, v106, v56
	v_add_f32_e64 v56, v104, v104
	v_add_f32_e64 v57, v105, v104
	v_mov_b32_e32 v47, v32
	v_add_f32_e32 v57, v57, v58
	v_add_f32_e32 v57, v56, v57
	v_add_f32_e32 v52, v56, v57
	v_mfma_f32_32x32x16_bf16 v[0:15], v[76:79], v[48:51], v[0:15]
	v_add_f32_e32 v52, v56, v52
	v_add_f32_e32 v52, v56, v52
	v_add_f32_e32 v52, v56, v52
	v_add_f32_e32 v52, v56, v52
	v_lshl_add_u64 v[48:49], v[154:155], 0, s[6:7]
	s_or_b32 s6, s34, s37
	v_add_f32_e32 v52, v56, v52
	s_add_u32 s6, s46, s6
	v_add_f32_e32 v52, v56, v52
	s_addc_u32 s7, s47, 0
	v_add_f32_e32 v173, 0, v52
	v_lshl_add_u64 v[156:157], v[48:49], 0, s[22:23]
	v_lshl_add_u64 v[158:159], s[6:7], 0, v[136:137]
	s_mov_b32 s60, -2
	s_branch .LBB0_765
.LBB0_764:
	s_add_i32 s60, s60, 1
	v_lshl_add_u64 v[156:157], v[156:157], 0, s[24:25]
	s_cmp_eq_u32 s30, s60
	v_lshl_add_u64 v[158:159], v[158:159], 0, s[26:27]
	s_cbranch_scc1 .LBB0_775

.LBB0_769:
	s_add_i32 s7, s60, 3
	s_and_b32 s6, s7, 3
	s_xor_b32 s34, s6, 2
	s_mul_i32 s35, s34, 0x3000
	s_add_i32 s36, s35, s55
	s_add_i32 s35, s59, s35
	s_lshl_b32 s34, s34, 13
	s_add_i32 s34, s58, s34
	s_cmp_le_u32 s57, s7
	s_cbranch_scc1 .Latt_inactive
	s_mul_i32 s7, s6, 0x3000
	v_add_u32_e32 v189, s7, v151
	v_lshl_add_u32 v188, s6, 13, v161
	ds_read_b128 v[196:199], v189
	ds_read_b128 v[204:207], v189 offset:2048
	ds_read_b128 v[212:215], v189 offset:4096
	ds_read_b128 v[220:223], v189 offset:6144
	ds_read_b128 v[228:231], v189 offset:8192
	ds_read_b128 v[236:239], v189 offset:10240
	ds_read_b128 v[200:203], v189 offset:512
	ds_read_b128 v[208:211], v189 offset:2560
	ds_read_b128 v[216:219], v189 offset:4608
	ds_read_b128 v[224:227], v189 offset:6656
	ds_read_b128 v[232:235], v189 offset:8704
	ds_read_b128 v[176:179], v189 offset:10752
	s_mov_b32 s37, m0
	s_waitcnt lgkmcnt(11)
	v_mfma_f32_32x32x16_bf16 v[64:79], v[196:199], v[92:95], v[32:47]
	s_waitcnt lgkmcnt(10)
	v_mfma_f32_32x32x16_bf16 v[64:79], v[204:207], v[88:91], v[64:79]
	s_mov_b32 m0, s36
	ds_read_b64_tr_b16 v[132:133], v188 offset:0
	ds_read_b64_tr_b16 v[134:135], v188 offset:512
	ds_read_b64_tr_b16 v[128:129], v188 offset:1024
	global_load_lds_dwordx4 v[158:159], off
	s_waitcnt lgkmcnt(12)
	v_mfma_f32_32x32x16_bf16 v[64:79], v[212:215], v[84:87], v[64:79]
	s_waitcnt lgkmcnt(11)
	v_mfma_f32_32x32x16_bf16 v[64:79], v[220:223], v[80:83], v[64:79]
	ds_read_b64_tr_b16 v[130:131], v188 offset:1536
	ds_read_b64_tr_b16 v[124:125], v188 offset:2048
	ds_read_b64_tr_b16 v[126:127], v188 offset:2560
	s_waitcnt lgkmcnt(13)
	v_mfma_f32_32x32x16_bf16 v[64:79], v[228:231], v[96:99], v[64:79]
	s_waitcnt lgkmcnt(12)
	v_mfma_f32_32x32x16_bf16 v[64:79], v[236:239], v[100:103], v[64:79]
	s_and_b64 vcc, exec, s[4:5]
	s_cbranch_vccnz .Latt_nok2
	v_lshl_add_u64 v[186:187], v[158:159], 0, s[12:13]
	s_mov_b32 m0, s35
	s_nop 0
	global_load_lds_dwordx4 v[186:187], off
.Latt_nok2:
	ds_read_b64_tr_b16 v[120:121], v188 offset:3072
	ds_read_b64_tr_b16 v[122:123], v188 offset:3584
	s_waitcnt lgkmcnt(13)
	v_mfma_f32_32x32x16_bf16 v[48:63], v[200:203], v[92:95], v[32:47]
	ds_read_b64_tr_b16 v[116:117], v188 offset:4096
	s_nop 1
	s_waitcnt lgkmcnt(13)
	v_mfma_f32_32x32x16_bf16 v[48:63], v[208:211], v[88:91], v[48:63]
	ds_read_b64_tr_b16 v[118:119], v188 offset:4608
	v_max3_f32 v136, v64, v65, v66
	v_max3_f32 v175, v67, v68, v69
	v_max3_f32 v136, v136, v70, v71
	v_max3_f32 v175, v175, v72, v73
	v_max3_f32 v136, v136, v74, v75
	v_max3_f32 v175, v175, v76, v77
	s_waitcnt lgkmcnt(13)
	v_mfma_f32_32x32x16_bf16 v[48:63], v[216:219], v[84:87], v[48:63]
	ds_read_b64_tr_b16 v[112:113], v188 offset:5120
	v_max3_f32 v136, v136, v78, v79
	v_exp_f32_e32 v196, v64
	v_exp_f32_e32 v197, v65
	v_exp_f32_e32 v198, v66
	v_exp_f32_e32 v199, v67
	v_add_f32_e32 v180, v196, v197
	v_add_f32_e32 v181, v198, v199
	v_exp_f32_e32 v204, v68
	v_exp_f32_e32 v205, v69
	s_waitcnt lgkmcnt(13)
	v_mfma_f32_32x32x16_bf16 v[48:63], v[224:227], v[80:83], v[48:63]
	ds_read_b64_tr_b16 v[114:115], v188 offset:5632
	s_mov_b32 m0, s34
	s_nop 0
	global_load_lds_dwordx4 v[156:157], off
	v_exp_f32_e32 v206, v70
	v_exp_f32_e32 v207, v71
	v_add_f32_e32 v180, v180, v204
	v_add_f32_e32 v181, v181, v205
	v_add_f32_e32 v180, v180, v206
	v_add_f32_e32 v181, v181, v207
	v_exp_f32_e32 v212, v72
	v_exp_f32_e32 v213, v73
	v_exp_f32_e32 v214, v74
	s_waitcnt lgkmcnt(13)
	v_mfma_f32_32x32x16_bf16 v[48:63], v[232:235], v[96:99], v[48:63]
	ds_read_b64_tr_b16 v[108:109], v188 offset:6144
	v_exp_f32_e32 v215, v75
	v_add_f32_e32 v180, v180, v212
	v_add_f32_e32 v181, v181, v213
	v_add_f32_e32 v180, v180, v214
	v_add_f32_e32 v181, v181, v215
	v_exp_f32_e32 v220, v76
	v_exp_f32_e32 v221, v77
	v_exp_f32_e32 v222, v78
	v_exp_f32_e32 v223, v79
	s_waitcnt lgkmcnt(13)
	v_mfma_f32_32x32x16_bf16 v[48:63], v[176:179], v[100:103], v[48:63]
	ds_read_b64_tr_b16 v[110:111], v188 offset:6656
	ds_read_b64_tr_b16 v[104:105], v188 offset:7168
	s_waitcnt lgkmcnt(14)
	ds_read_b64_tr_b16 v[106:107], v188 offset:7680
	s_mov_b32 m0, s37
	v_add_f32_e32 v180, v180, v220
	v_add_f32_e32 v181, v181, v221
	v_add_f32_e32 v180, v180, v222
	v_add_f32_e32 v181, v181, v223
	v_cvt_pk_bf16_f32 v228, v196, v197
	v_cvt_pk_bf16_f32 v229, v198, v199
	v_cvt_pk_bf16_f32 v230, v204, v205
	v_cvt_pk_bf16_f32 v231, v206, v207
	v_cvt_pk_bf16_f32 v236, v212, v213
	v_cvt_pk_bf16_f32 v237, v214, v215
	v_cvt_pk_bf16_f32 v238, v220, v221
	v_cvt_pk_bf16_f32 v239, v222, v223
	v_add_f32_e32 v180, v180, v181
	s_nop 2
	v_max3_f32 v175, v175, v48, v49
	v_max3_f32 v136, v136, v50, v51
	v_max3_f32 v175, v175, v52, v53
	v_max3_f32 v136, v136, v54, v55
	v_max3_f32 v175, v175, v56, v57
	v_max3_f32 v136, v136, v58, v59
	v_max3_f32 v175, v175, v60, v61
	v_max3_f32 v136, v136, v62, v63
	v_max_f32_e32 v136, v136, v175
	v_mov_b32_e32 v175, v136
	s_nop 1
	v_permlane32_swap_b32_e32 v136, v175
	v_max_f32_e32 v136, v136, v175
	s_nop 0
	v_cmp_lt_f32_e32 vcc, s51, v136
	s_cbranch_vccnz .Latt_rare
.Latt_cont:
	s_waitcnt lgkmcnt(0)
	v_mfma_f32_32x32x16_bf16 v[16:31], v[228:231], v[132:135], v[16:31]
	v_exp_f32_e32 v48, v48
	v_exp_f32_e32 v49, v49
	v_exp_f32_e32 v50, v50
	v_exp_f32_e32 v51, v51
	v_add_f32_e32 v182, v48, v49
	v_add_f32_e32 v183, v50, v51
	v_exp_f32_e32 v52, v52
	v_exp_f32_e32 v53, v53
	v_exp_f32_e32 v54, v54
	v_exp_f32_e32 v55, v55
	v_add_f32_e32 v182, v182, v52
	v_mfma_f32_32x32x16_bf16 v[0:15], v[228:231], v[116:119], v[0:15]
	v_add_f32_e32 v183, v183, v53
	v_add_f32_e32 v182, v182, v54
	v_add_f32_e32 v183, v183, v55
	v_cvt_pk_bf16_f32 v48, v48, v49
	v_cvt_pk_bf16_f32 v49, v50, v51
	v_cvt_pk_bf16_f32 v50, v52, v53
	v_cvt_pk_bf16_f32 v51, v54, v55
	v_exp_f32_e32 v56, v56
	v_exp_f32_e32 v57, v57
	v_exp_f32_e32 v58, v58
	v_exp_f32_e32 v59, v59
	v_mfma_f32_32x32x16_bf16 v[16:31], v[236:239], v[128:131], v[16:31]
	v_add_f32_e32 v182, v182, v56
	v_add_f32_e32 v183, v183, v57
	v_add_f32_e32 v182, v182, v58
	v_add_f32_e32 v183, v183, v59
	v_exp_f32_e32 v60, v60
	v_exp_f32_e32 v61, v61
	v_exp_f32_e32 v62, v62
	v_exp_f32_e32 v63, v63
	v_add_f32_e32 v182, v182, v60
	v_add_f32_e32 v183, v183, v61
	v_add_f32_e32 v182, v182, v62
	v_mfma_f32_32x32x16_bf16 v[0:15], v[236:239], v[112:115], v[0:15]
	v_add_f32_e32 v183, v183, v63
	v_cvt_pk_bf16_f32 v52, v56, v57
	v_cvt_pk_bf16_f32 v53, v58, v59
	v_cvt_pk_bf16_f32 v54, v60, v61
	v_cvt_pk_bf16_f32 v55, v62, v63
	v_add_f32_e32 v182, v182, v183
	v_add_f32_e32 v180, v180, v182
	v_add_f32_e32 v173, v173, v180
	s_nop 0
	v_mfma_f32_32x32x16_bf16 v[16:31], v[48:51], v[124:127], v[16:31]
	v_mfma_f32_32x32x16_bf16 v[0:15], v[48:51], v[108:111], v[0:15]
	v_mfma_f32_32x32x16_bf16 v[16:31], v[52:55], v[120:123], v[16:31]
	v_mfma_f32_32x32x16_bf16 v[0:15], v[52:55], v[104:107], v[0:15]
	s_branch .LBB0_764
.Latt_rare:
	v_max_f32_e32 v32, v136, v136
	v_max_f32_e32 v34, 0, v32
	v_exp_f32_e64 v136, -v34
	s_and_saveexec_b64 s[6:7], s[0:1]
	ds_write_b32 v171, v136
	s_or_b64 exec, exec, s[6:7]
	s_waitcnt lgkmcnt(0)
	ds_read_b128 v[176:179], v172 offset:64
	ds_read_b128 v[180:183], v172 offset:96
	ds_read_b128 v[184:187], v172
	ds_read_b128 v[192:195], v172 offset:32
	v_add_f32_e32 v174, v174, v34
	v_xor_b32_e32 v32, 0x80000000, v174
	v_pk_add_f32 v[64:65], v[64:65], v[34:35] op_sel_hi:[1,0] neg_lo:[0,1] neg_hi:[0,1]
	v_pk_add_f32 v[48:49], v[48:49], v[34:35] op_sel_hi:[1,0] neg_lo:[0,1] neg_hi:[0,1]
	v_pk_add_f32 v[66:67], v[66:67], v[34:35] op_sel_hi:[1,0] neg_lo:[0,1] neg_hi:[0,1]
	v_pk_add_f32 v[50:51], v[50:51], v[34:35] op_sel_hi:[1,0] neg_lo:[0,1] neg_hi:[0,1]
	v_pk_add_f32 v[68:69], v[68:69], v[34:35] op_sel_hi:[1,0] neg_lo:[0,1] neg_hi:[0,1]
	v_pk_add_f32 v[52:53], v[52:53], v[34:35] op_sel_hi:[1,0] neg_lo:[0,1] neg_hi:[0,1]
	v_pk_add_f32 v[70:71], v[70:71], v[34:35] op_sel_hi:[1,0] neg_lo:[0,1] neg_hi:[0,1]
	v_pk_add_f32 v[54:55], v[54:55], v[34:35] op_sel_hi:[1,0] neg_lo:[0,1] neg_hi:[0,1]
	v_pk_add_f32 v[72:73], v[72:73], v[34:35] op_sel_hi:[1,0] neg_lo:[0,1] neg_hi:[0,1]
	v_pk_add_f32 v[56:57], v[56:57], v[34:35] op_sel_hi:[1,0] neg_lo:[0,1] neg_hi:[0,1]
	v_pk_add_f32 v[74:75], v[74:75], v[34:35] op_sel_hi:[1,0] neg_lo:[0,1] neg_hi:[0,1]
	v_pk_add_f32 v[58:59], v[58:59], v[34:35] op_sel_hi:[1,0] neg_lo:[0,1] neg_hi:[0,1]
	v_pk_add_f32 v[76:77], v[76:77], v[34:35] op_sel_hi:[1,0] neg_lo:[0,1] neg_hi:[0,1]
	v_pk_add_f32 v[60:61], v[60:61], v[34:35] op_sel_hi:[1,0] neg_lo:[0,1] neg_hi:[0,1]
	v_pk_add_f32 v[78:79], v[78:79], v[34:35] op_sel_hi:[1,0] neg_lo:[0,1] neg_hi:[0,1]
	v_pk_add_f32 v[62:63], v[62:63], v[34:35] op_sel_hi:[1,0] neg_lo:[0,1] neg_hi:[0,1]
	v_mul_f32_e32 v173, v173, v136
	v_exp_f32_e32 v196, v64
	v_exp_f32_e32 v197, v65
	v_exp_f32_e32 v198, v66
	v_exp_f32_e32 v199, v67
	v_exp_f32_e32 v204, v68
	v_exp_f32_e32 v205, v69
	v_exp_f32_e32 v206, v70
	v_exp_f32_e32 v207, v71
	v_exp_f32_e32 v212, v72
	v_exp_f32_e32 v213, v73
	v_exp_f32_e32 v214, v74
	v_exp_f32_e32 v215, v75
	v_exp_f32_e32 v220, v76
	v_exp_f32_e32 v221, v77
	v_exp_f32_e32 v222, v78
	v_exp_f32_e32 v223, v79
	s_waitcnt lgkmcnt(0)
	v_pk_mul_f32 v[28:29], v[28:29], v[180:181]
	v_pk_mul_f32 v[24:25], v[24:25], v[176:177]
	v_pk_mul_f32 v[20:21], v[20:21], v[192:193]
	v_pk_mul_f32 v[30:31], v[30:31], v[182:183]
	v_pk_mul_f32 v[26:27], v[26:27], v[178:179]
	v_pk_mul_f32 v[22:23], v[22:23], v[194:195]
	v_pk_mul_f32 v[18:19], v[18:19], v[186:187]
	v_pk_mul_f32 v[16:17], v[16:17], v[184:185]
	v_pk_mul_f32 v[12:13], v[12:13], v[180:181]
	v_pk_mul_f32 v[8:9], v[8:9], v[176:177]
	v_pk_mul_f32 v[4:5], v[4:5], v[192:193]
	v_pk_mul_f32 v[14:15], v[14:15], v[182:183]
	v_pk_mul_f32 v[10:11], v[10:11], v[178:179]
	v_pk_mul_f32 v[6:7], v[6:7], v[194:195]
	v_pk_mul_f32 v[2:3], v[2:3], v[186:187]
	v_pk_mul_f32 v[0:1], v[0:1], v[184:185]
	v_mov_b32_e32 v33, v32
	v_mov_b32_e32 v34, v32
	v_mov_b32_e32 v35, v32
	v_mov_b32_e32 v36, v32
	v_mov_b32_e32 v37, v32
	v_mov_b32_e32 v38, v32
	v_mov_b32_e32 v39, v32
	v_mov_b32_e32 v40, v32
	v_mov_b32_e32 v41, v32
	v_mov_b32_e32 v42, v32
	v_mov_b32_e32 v43, v32
	v_mov_b32_e32 v44, v32
	v_mov_b32_e32 v45, v32
	v_mov_b32_e32 v46, v32
	v_mov_b32_e32 v47, v32
	v_add_f32_e32 v180, v196, v197
	v_add_f32_e32 v181, v198, v199
	v_add_f32_e32 v180, v180, v204
	v_add_f32_e32 v181, v181, v205
	v_add_f32_e32 v180, v180, v206
	v_add_f32_e32 v181, v181, v207
	v_add_f32_e32 v180, v180, v212
	v_add_f32_e32 v181, v181, v213
	v_add_f32_e32 v180, v180, v214
	v_add_f32_e32 v181, v181, v215
	v_add_f32_e32 v180, v180, v220
	v_add_f32_e32 v181, v181, v221
	v_add_f32_e32 v180, v180, v222
	v_add_f32_e32 v181, v181, v223
	v_cvt_pk_bf16_f32 v228, v196, v197
	v_cvt_pk_bf16_f32 v229, v198, v199
	v_cvt_pk_bf16_f32 v230, v204, v205
	v_cvt_pk_bf16_f32 v231, v206, v207
	v_cvt_pk_bf16_f32 v236, v212, v213
	v_cvt_pk_bf16_f32 v237, v214, v215
	v_cvt_pk_bf16_f32 v238, v220, v221
	v_cvt_pk_bf16_f32 v239, v222, v223
	v_add_f32_e32 v180, v180, v181
	s_branch .Latt_cont
.Latt_inactive:
	s_mov_b32 s37, m0
	s_mov_b32 m0, s36
	s_nop 0
	global_load_lds_dwordx4 v[158:159], off
	s_and_b64 vcc, exec, s[4:5]
	s_cbranch_vccnz .Latt_inact_b
	v_lshl_add_u64 v[186:187], v[158:159], 0, s[12:13]
	s_mov_b32 m0, s35
	s_nop 0
	global_load_lds_dwordx4 v[186:187], off

.LBB0_890:
	v_lshl_add_u32 v2, s36, 8, v161
	s_cmp_lg_u32 s62, 0
	v_ashrrev_i32_e32 v3, 31, v2
	s_cselect_b64 s[34:35], -1, 0
	v_lshlrev_b64 v[158:159], 11, v[2:3]
	v_lshl_or_b32 v146, s37, 8, v163
	v_or_b32_e32 v152, 16, v2
	v_or_b32_e32 v150, 32, v2
	v_or_b32_e32 v148, 48, v2
	v_lshl_add_u64 v[154:155], s[6:7], 0, v[158:159]
	s_and_b64 vcc, exec, s[34:35]
	v_ashrrev_i32_e32 v147, 31, v146
	v_ashrrev_i32_e32 v153, 31, v152
	v_ashrrev_i32_e32 v151, 31, v150
	v_ashrrev_i32_e32 v149, 31, v148
	s_cbranch_vccz .LBB0_898
	v_lshl_add_u64 v[170:171], v[154:155], 0, v[146:147]
	v_add_u32_e32 v234, v158, v146
	global_load_dwordx2 v[202:203], v234, s[6:7] offset:1024
	global_load_dwordx2 v[204:205], v234, s[6:7] offset:1152
	v_add_u32_e32 v235, 0x8000, v234
	global_load_dwordx2 v[206:207], v235, s[6:7] offset:1024
	global_load_dwordx2 v[208:209], v235, s[6:7] offset:1152
	v_add_u32_e32 v235, 0x10000, v234
	global_load_dwordx2 v[210:211], v235, s[6:7] offset:1024
	global_load_dwordx2 v[212:213], v235, s[6:7] offset:1152
	v_add_u32_e32 v235, 0x18000, v234
	global_load_dwordx2 v[214:215], v235, s[6:7] offset:1024
	global_load_dwordx2 v[216:217], v235, s[6:7] offset:1152
	v_add_u32_e32 v235, 0x40000, v234
	global_load_dwordx2 v[218:219], v235, s[6:7] offset:1024
	global_load_dwordx2 v[220:221], v235, s[6:7] offset:1152
	v_add_u32_e32 v235, 0x48000, v234
	global_load_dwordx2 v[222:223], v235, s[6:7] offset:1024
	global_load_dwordx2 v[224:225], v235, s[6:7] offset:1152
	v_add_u32_e32 v235, 0x50000, v234
	global_load_dwordx2 v[226:227], v235, s[6:7] offset:1024
	global_load_dwordx2 v[228:229], v235, s[6:7] offset:1152
	v_add_u32_e32 v235, 0x58000, v234
	global_load_dwordx2 v[230:231], v235, s[6:7] offset:1024
	global_load_dwordx2 v[232:233], v235, s[6:7] offset:1152
	v_lshl_add_u64 v[168:169], s[8:9], 0, v[158:159]
	v_lshlrev_b64 v[156:157], 1, v[146:147]
	v_lshl_add_u64 v[172:173], v[168:169], 0, v[156:157]
	s_waitcnt vmcnt(15)
	v_mov_b32_e32 v166, v202
	v_mov_b32_e32 v167, v203
	v_max_u32_sdwa v168, v167, v165 dst_sel:DWORD dst_unused:UNUSED_PAD src0_sel:BYTE_0 src1_sel:DWORD
	v_max_u32_sdwa v169, v166, v165 dst_sel:DWORD dst_unused:UNUSED_PAD src0_sel:BYTE_1 src1_sel:DWORD
	v_max_u32_sdwa v1, v166, v165 dst_sel:DWORD dst_unused:UNUSED_PAD src0_sel:BYTE_0 src1_sel:DWORD
	v_max_u32_sdwa v174, v167, v165 dst_sel:DWORD dst_unused:UNUSED_PAD src0_sel:BYTE_1 src1_sel:DWORD
	v_max_u32_sdwa v175, v166, v165 dst_sel:DWORD dst_unused:UNUSED_PAD src0_sel:BYTE_2 src1_sel:DWORD
	v_max_u32_sdwa v176, v167, v165 dst_sel:DWORD dst_unused:UNUSED_PAD src0_sel:BYTE_2 src1_sel:DWORD
	v_max_u32_sdwa v166, v166, v165 dst_sel:DWORD dst_unused:UNUSED_PAD src0_sel:BYTE_3 src1_sel:DWORD
	v_max_u32_sdwa v167, v167, v165 dst_sel:DWORD dst_unused:UNUSED_PAD src0_sel:BYTE_3 src1_sel:DWORD
	v_cvt_f32_ubyte0_e32 v168, v168
	v_cvt_f32_ubyte0_e32 v169, v169
	v_cvt_f32_ubyte0_e32 v1, v1
	v_cvt_f32_ubyte0_e32 v174, v174
	v_cvt_f32_ubyte0_e32 v175, v175
	v_cvt_f32_ubyte0_e32 v176, v176
	v_cvt_f32_ubyte0_e32 v166, v166
	v_cvt_f32_ubyte0_e32 v167, v167
	v_mul_f32_e32 v168, 0x3b808081, v168
	v_mul_f32_e32 v169, 0x3b808081, v169
	v_mul_f32_e32 v1, 0x3b808081, v1
	v_mul_f32_e32 v174, 0x3b808081, v174
	v_mul_f32_e32 v175, 0x3b808081, v175
	v_mul_f32_e32 v176, 0x3b808081, v176
	v_mul_f32_e32 v166, 0x3b808081, v166
	v_mul_f32_e32 v167, 0x3b808081, v167
	v_mul_f32_e32 v168, v124, v168
	v_mul_f32_e32 v169, v129, v169
	v_mul_f32_e32 v1, v128, v1
	v_mul_f32_e32 v174, v125, v174
	v_mul_f32_e32 v175, v130, v175
	v_mul_f32_e32 v176, v126, v176
	v_mul_f32_e32 v177, v131, v166
	v_mul_f32_e32 v178, v127, v167
	v_cvt_pk_bf16_f32 v166, v1, v169
	v_cvt_pk_bf16_f32 v167, v175, v177
	v_cvt_pk_bf16_f32 v168, v168, v174
	v_cvt_pk_bf16_f32 v169, v176, v178
	global_store_dwordx4 v[172:173], v[166:169], off
	s_nop 0
	v_lshlrev_b64 v[170:171], 11, v[152:153]
	v_lshl_add_u64 v[168:169], s[6:7], 0, v[170:171]
	v_lshl_add_u64 v[174:175], v[168:169], 0, v[146:147]
	s_waitcnt vmcnt(15)
	v_mov_b32_e32 v166, v204
	v_mov_b32_e32 v167, v205
	v_max_u32_sdwa v168, v167, v165 dst_sel:DWORD dst_unused:UNUSED_PAD src0_sel:BYTE_0 src1_sel:DWORD
	v_max_u32_sdwa v169, v166, v165 dst_sel:DWORD dst_unused:UNUSED_PAD src0_sel:BYTE_1 src1_sel:DWORD
	v_max_u32_sdwa v1, v166, v165 dst_sel:DWORD dst_unused:UNUSED_PAD src0_sel:BYTE_0 src1_sel:DWORD
	v_max_u32_sdwa v176, v167, v165 dst_sel:DWORD dst_unused:UNUSED_PAD src0_sel:BYTE_1 src1_sel:DWORD
	v_max_u32_sdwa v177, v166, v165 dst_sel:DWORD dst_unused:UNUSED_PAD src0_sel:BYTE_2 src1_sel:DWORD
	v_max_u32_sdwa v178, v167, v165 dst_sel:DWORD dst_unused:UNUSED_PAD src0_sel:BYTE_2 src1_sel:DWORD
	v_max_u32_sdwa v166, v166, v165 dst_sel:DWORD dst_unused:UNUSED_PAD src0_sel:BYTE_3 src1_sel:DWORD
	v_max_u32_sdwa v167, v167, v165 dst_sel:DWORD dst_unused:UNUSED_PAD src0_sel:BYTE_3 src1_sel:DWORD
	v_cvt_f32_ubyte0_e32 v168, v168
	v_cvt_f32_ubyte0_e32 v169, v169
	v_cvt_f32_ubyte0_e32 v1, v1
	v_cvt_f32_ubyte0_e32 v176, v176
	v_cvt_f32_ubyte0_e32 v177, v177
	v_cvt_f32_ubyte0_e32 v178, v178
	v_cvt_f32_ubyte0_e32 v166, v166
	v_cvt_f32_ubyte0_e32 v167, v167
	v_mul_f32_e32 v168, 0x3b808081, v168
	v_mul_f32_e32 v169, 0x3b808081, v169
	v_mul_f32_e32 v1, 0x3b808081, v1
	v_mul_f32_e32 v176, 0x3b808081, v176
	v_mul_f32_e32 v177, 0x3b808081, v177
	v_mul_f32_e32 v178, 0x3b808081, v178
	v_mul_f32_e32 v166, 0x3b808081, v166
	v_mul_f32_e32 v167, 0x3b808081, v167
	v_mul_f32_e32 v168, v92, v168
	v_mul_f32_e32 v169, v97, v169
	v_mul_f32_e32 v1, v96, v1
	v_mul_f32_e32 v176, v93, v176
	v_mul_f32_e32 v177, v98, v177
	v_mul_f32_e32 v178, v94, v178
	v_mul_f32_e32 v179, v99, v166
	v_mul_f32_e32 v180, v95, v167
	v_cvt_pk_bf16_f32 v166, v1, v169
	v_cvt_pk_bf16_f32 v167, v177, v179
	v_cvt_pk_bf16_f32 v168, v168, v176
	v_cvt_pk_bf16_f32 v169, v178, v180
	global_store_dwordx4 v[172:173], v[166:169], off offset:256
	s_nop 0
	s_waitcnt vmcnt(15)
	v_mov_b32_e32 v166, v206
	v_mov_b32_e32 v167, v207
	v_max_u32_sdwa v1, v166, v165 dst_sel:DWORD dst_unused:UNUSED_PAD src0_sel:BYTE_0 src1_sel:DWORD
	v_lshl_add_u64 v[168:169], s[8:9], 0, v[170:171]
	v_lshl_add_u64 v[170:171], v[168:169], 0, v[156:157]
	v_max_u32_sdwa v168, v167, v165 dst_sel:DWORD dst_unused:UNUSED_PAD src0_sel:BYTE_0 src1_sel:DWORD
	v_max_u32_sdwa v169, v166, v165 dst_sel:DWORD dst_unused:UNUSED_PAD src0_sel:BYTE_1 src1_sel:DWORD
	v_max_u32_sdwa v172, v167, v165 dst_sel:DWORD dst_unused:UNUSED_PAD src0_sel:BYTE_1 src1_sel:DWORD
	v_max_u32_sdwa v173, v166, v165 dst_sel:DWORD dst_unused:UNUSED_PAD src0_sel:BYTE_2 src1_sel:DWORD
	v_max_u32_sdwa v176, v167, v165 dst_sel:DWORD dst_unused:UNUSED_PAD src0_sel:BYTE_2 src1_sel:DWORD
	v_max_u32_sdwa v166, v166, v165 dst_sel:DWORD dst_unused:UNUSED_PAD src0_sel:BYTE_3 src1_sel:DWORD
	v_max_u32_sdwa v167, v167, v165 dst_sel:DWORD dst_unused:UNUSED_PAD src0_sel:BYTE_3 src1_sel:DWORD
	v_cvt_f32_ubyte0_e32 v168, v168
	v_cvt_f32_ubyte0_e32 v169, v169
	v_cvt_f32_ubyte0_e32 v1, v1
	v_cvt_f32_ubyte0_e32 v172, v172
	v_cvt_f32_ubyte0_e32 v173, v173
	v_cvt_f32_ubyte0_e32 v176, v176
	v_cvt_f32_ubyte0_e32 v166, v166
	v_cvt_f32_ubyte0_e32 v167, v167
	v_mul_f32_e32 v168, 0x3b808081, v168
	v_mul_f32_e32 v169, 0x3b808081, v169
	v_mul_f32_e32 v1, 0x3b808081, v1
	v_mul_f32_e32 v172, 0x3b808081, v172
	v_mul_f32_e32 v173, 0x3b808081, v173
	v_mul_f32_e32 v176, 0x3b808081, v176
	v_mul_f32_e32 v166, 0x3b808081, v166
	v_mul_f32_e32 v167, 0x3b808081, v167
	v_mul_f32_e32 v168, v116, v168
	v_mul_f32_e32 v169, v121, v169
	v_mul_f32_e32 v1, v120, v1
	v_mul_f32_e32 v172, v117, v172
	v_mul_f32_e32 v173, v122, v173
	v_mul_f32_e32 v176, v118, v176
	v_mul_f32_e32 v177, v123, v166
	v_mul_f32_e32 v178, v119, v167
	v_cvt_pk_bf16_f32 v166, v1, v169
	v_cvt_pk_bf16_f32 v167, v173, v177
	v_cvt_pk_bf16_f32 v168, v168, v172
	v_cvt_pk_bf16_f32 v169, v176, v178
	global_store_dwordx4 v[170:171], v[166:169], off
	s_nop 0
	v_lshlrev_b64 v[172:173], 11, v[150:151]
	v_lshl_add_u64 v[168:169], s[6:7], 0, v[172:173]
	v_lshl_add_u64 v[174:175], v[168:169], 0, v[146:147]
	s_waitcnt vmcnt(15)
	v_mov_b32_e32 v166, v208
	v_mov_b32_e32 v167, v209
	v_max_u32_sdwa v168, v167, v165 dst_sel:DWORD dst_unused:UNUSED_PAD src0_sel:BYTE_0 src1_sel:DWORD
	v_max_u32_sdwa v169, v166, v165 dst_sel:DWORD dst_unused:UNUSED_PAD src0_sel:BYTE_1 src1_sel:DWORD
	v_max_u32_sdwa v1, v166, v165 dst_sel:DWORD dst_unused:UNUSED_PAD src0_sel:BYTE_0 src1_sel:DWORD
	v_max_u32_sdwa v176, v167, v165 dst_sel:DWORD dst_unused:UNUSED_PAD src0_sel:BYTE_1 src1_sel:DWORD
	v_max_u32_sdwa v177, v166, v165 dst_sel:DWORD dst_unused:UNUSED_PAD src0_sel:BYTE_2 src1_sel:DWORD
	v_max_u32_sdwa v178, v167, v165 dst_sel:DWORD dst_unused:UNUSED_PAD src0_sel:BYTE_2 src1_sel:DWORD
	v_max_u32_sdwa v166, v166, v165 dst_sel:DWORD dst_unused:UNUSED_PAD src0_sel:BYTE_3 src1_sel:DWORD
	v_max_u32_sdwa v167, v167, v165 dst_sel:DWORD dst_unused:UNUSED_PAD src0_sel:BYTE_3 src1_sel:DWORD
	v_cvt_f32_ubyte0_e32 v168, v168
	v_cvt_f32_ubyte0_e32 v169, v169
	v_cvt_f32_ubyte0_e32 v1, v1
	v_cvt_f32_ubyte0_e32 v176, v176
	v_cvt_f32_ubyte0_e32 v177, v177
	v_cvt_f32_ubyte0_e32 v178, v178
	v_cvt_f32_ubyte0_e32 v166, v166
	v_cvt_f32_ubyte0_e32 v167, v167
	v_mul_f32_e32 v168, 0x3b808081, v168
	v_mul_f32_e32 v169, 0x3b808081, v169
	v_mul_f32_e32 v1, 0x3b808081, v1
	v_mul_f32_e32 v176, 0x3b808081, v176
	v_mul_f32_e32 v177, 0x3b808081, v177
	v_mul_f32_e32 v178, 0x3b808081, v178
	v_mul_f32_e32 v166, 0x3b808081, v166
	v_mul_f32_e32 v167, 0x3b808081, v167
	v_mul_f32_e32 v168, v84, v168
	v_mul_f32_e32 v169, v89, v169
	v_mul_f32_e32 v1, v88, v1
	v_mul_f32_e32 v176, v85, v176
	v_mul_f32_e32 v177, v90, v177
	v_mul_f32_e32 v178, v86, v178
	v_mul_f32_e32 v179, v91, v166
	v_mul_f32_e32 v180, v87, v167
	v_cvt_pk_bf16_f32 v166, v1, v169
	v_cvt_pk_bf16_f32 v167, v177, v179
	v_cvt_pk_bf16_f32 v168, v168, v176
	v_cvt_pk_bf16_f32 v169, v178, v180
	global_store_dwordx4 v[170:171], v[166:169], off offset:256
	s_nop 0
	s_waitcnt vmcnt(15)
	v_mov_b32_e32 v166, v210
	v_mov_b32_e32 v167, v211
	v_max_u32_sdwa v1, v166, v165 dst_sel:DWORD dst_unused:UNUSED_PAD src0_sel:BYTE_0 src1_sel:DWORD
	v_lshl_add_u64 v[168:169], s[8:9], 0, v[172:173]
	v_lshl_add_u64 v[170:171], v[168:169], 0, v[156:157]
	v_max_u32_sdwa v168, v167, v165 dst_sel:DWORD dst_unused:UNUSED_PAD src0_sel:BYTE_0 src1_sel:DWORD
	v_max_u32_sdwa v169, v166, v165 dst_sel:DWORD dst_unused:UNUSED_PAD src0_sel:BYTE_1 src1_sel:DWORD
	v_max_u32_sdwa v172, v167, v165 dst_sel:DWORD dst_unused:UNUSED_PAD src0_sel:BYTE_1 src1_sel:DWORD
	v_max_u32_sdwa v173, v166, v165 dst_sel:DWORD dst_unused:UNUSED_PAD src0_sel:BYTE_2 src1_sel:DWORD
	v_max_u32_sdwa v176, v167, v165 dst_sel:DWORD dst_unused:UNUSED_PAD src0_sel:BYTE_2 src1_sel:DWORD
	v_max_u32_sdwa v166, v166, v165 dst_sel:DWORD dst_unused:UNUSED_PAD src0_sel:BYTE_3 src1_sel:DWORD
	v_max_u32_sdwa v167, v167, v165 dst_sel:DWORD dst_unused:UNUSED_PAD src0_sel:BYTE_3 src1_sel:DWORD
	v_cvt_f32_ubyte0_e32 v168, v168
	v_cvt_f32_ubyte0_e32 v169, v169
	v_cvt_f32_ubyte0_e32 v1, v1
	v_cvt_f32_ubyte0_e32 v172, v172
	v_cvt_f32_ubyte0_e32 v173, v173
	v_cvt_f32_ubyte0_e32 v176, v176
	v_cvt_f32_ubyte0_e32 v166, v166
	v_cvt_f32_ubyte0_e32 v167, v167
	v_mul_f32_e32 v168, 0x3b808081, v168
	v_mul_f32_e32 v169, 0x3b808081, v169
	v_mul_f32_e32 v1, 0x3b808081, v1
	v_mul_f32_e32 v172, 0x3b808081, v172
	v_mul_f32_e32 v173, 0x3b808081, v173
	v_mul_f32_e32 v176, 0x3b808081, v176
	v_mul_f32_e32 v166, 0x3b808081, v166
	v_mul_f32_e32 v167, 0x3b808081, v167
	v_mul_f32_e32 v168, v108, v168
	v_mul_f32_e32 v169, v113, v169
	v_mul_f32_e32 v1, v112, v1
	v_mul_f32_e32 v172, v109, v172
	v_mul_f32_e32 v173, v114, v173
	v_mul_f32_e32 v176, v110, v176
	v_mul_f32_e32 v177, v115, v166
	v_mul_f32_e32 v178, v111, v167
	v_cvt_pk_bf16_f32 v166, v1, v169
	v_cvt_pk_bf16_f32 v167, v173, v177
	v_cvt_pk_bf16_f32 v168, v168, v172
	v_cvt_pk_bf16_f32 v169, v176, v178
	global_store_dwordx4 v[170:171], v[166:169], off
	s_nop 0
	v_lshlrev_b64 v[172:173], 11, v[148:149]
	v_lshl_add_u64 v[168:169], s[6:7], 0, v[172:173]
	v_lshl_add_u64 v[174:175], v[168:169], 0, v[146:147]
	s_waitcnt vmcnt(15)
	v_mov_b32_e32 v166, v212
	v_mov_b32_e32 v167, v213
	v_max_u32_sdwa v168, v167, v165 dst_sel:DWORD dst_unused:UNUSED_PAD src0_sel:BYTE_0 src1_sel:DWORD
	v_max_u32_sdwa v169, v166, v165 dst_sel:DWORD dst_unused:UNUSED_PAD src0_sel:BYTE_1 src1_sel:DWORD
	v_max_u32_sdwa v1, v166, v165 dst_sel:DWORD dst_unused:UNUSED_PAD src0_sel:BYTE_0 src1_sel:DWORD
	v_max_u32_sdwa v176, v167, v165 dst_sel:DWORD dst_unused:UNUSED_PAD src0_sel:BYTE_1 src1_sel:DWORD
	v_max_u32_sdwa v177, v166, v165 dst_sel:DWORD dst_unused:UNUSED_PAD src0_sel:BYTE_2 src1_sel:DWORD
	v_max_u32_sdwa v178, v167, v165 dst_sel:DWORD dst_unused:UNUSED_PAD src0_sel:BYTE_2 src1_sel:DWORD
	v_max_u32_sdwa v166, v166, v165 dst_sel:DWORD dst_unused:UNUSED_PAD src0_sel:BYTE_3 src1_sel:DWORD
	v_max_u32_sdwa v167, v167, v165 dst_sel:DWORD dst_unused:UNUSED_PAD src0_sel:BYTE_3 src1_sel:DWORD
	v_cvt_f32_ubyte0_e32 v168, v168
	v_cvt_f32_ubyte0_e32 v169, v169
	v_cvt_f32_ubyte0_e32 v1, v1
	v_cvt_f32_ubyte0_e32 v176, v176
	v_cvt_f32_ubyte0_e32 v177, v177
	v_cvt_f32_ubyte0_e32 v178, v178
	v_cvt_f32_ubyte0_e32 v166, v166
	v_cvt_f32_ubyte0_e32 v167, v167
	v_mul_f32_e32 v168, 0x3b808081, v168
	v_mul_f32_e32 v169, 0x3b808081, v169
	v_mul_f32_e32 v1, 0x3b808081, v1
	v_mul_f32_e32 v176, 0x3b808081, v176
	v_mul_f32_e32 v177, 0x3b808081, v177
	v_mul_f32_e32 v178, 0x3b808081, v178
	v_mul_f32_e32 v166, 0x3b808081, v166
	v_mul_f32_e32 v167, 0x3b808081, v167
	v_mul_f32_e32 v168, v76, v168
	v_mul_f32_e32 v169, v81, v169
	v_mul_f32_e32 v1, v80, v1
	v_mul_f32_e32 v176, v77, v176
	v_mul_f32_e32 v177, v82, v177
	v_mul_f32_e32 v178, v78, v178
	v_mul_f32_e32 v179, v83, v166
	v_mul_f32_e32 v180, v79, v167
	v_cvt_pk_bf16_f32 v166, v1, v169
	v_cvt_pk_bf16_f32 v167, v177, v179
	v_cvt_pk_bf16_f32 v168, v168, v176
	v_cvt_pk_bf16_f32 v169, v178, v180
	global_store_dwordx4 v[170:171], v[166:169], off offset:256
	s_nop 0
	s_waitcnt vmcnt(15)
	v_mov_b32_e32 v166, v214
	v_mov_b32_e32 v167, v215
	v_max_u32_sdwa v1, v166, v165 dst_sel:DWORD dst_unused:UNUSED_PAD src0_sel:BYTE_0 src1_sel:DWORD
	v_lshl_add_u64 v[168:169], s[8:9], 0, v[172:173]
	v_lshl_add_u64 v[170:171], v[168:169], 0, v[156:157]
	v_max_u32_sdwa v168, v167, v165 dst_sel:DWORD dst_unused:UNUSED_PAD src0_sel:BYTE_0 src1_sel:DWORD
	v_max_u32_sdwa v169, v166, v165 dst_sel:DWORD dst_unused:UNUSED_PAD src0_sel:BYTE_1 src1_sel:DWORD
	v_max_u32_sdwa v172, v167, v165 dst_sel:DWORD dst_unused:UNUSED_PAD src0_sel:BYTE_1 src1_sel:DWORD
	v_max_u32_sdwa v173, v166, v165 dst_sel:DWORD dst_unused:UNUSED_PAD src0_sel:BYTE_2 src1_sel:DWORD
	v_max_u32_sdwa v176, v167, v165 dst_sel:DWORD dst_unused:UNUSED_PAD src0_sel:BYTE_2 src1_sel:DWORD
	v_max_u32_sdwa v166, v166, v165 dst_sel:DWORD dst_unused:UNUSED_PAD src0_sel:BYTE_3 src1_sel:DWORD
	v_max_u32_sdwa v167, v167, v165 dst_sel:DWORD dst_unused:UNUSED_PAD src0_sel:BYTE_3 src1_sel:DWORD
	v_cvt_f32_ubyte0_e32 v168, v168
	v_cvt_f32_ubyte0_e32 v169, v169
	v_cvt_f32_ubyte0_e32 v1, v1
	v_cvt_f32_ubyte0_e32 v172, v172
	v_cvt_f32_ubyte0_e32 v173, v173
	v_cvt_f32_ubyte0_e32 v176, v176
	v_cvt_f32_ubyte0_e32 v166, v166
	v_cvt_f32_ubyte0_e32 v167, v167
	v_mul_f32_e32 v168, 0x3b808081, v168
	v_mul_f32_e32 v169, 0x3b808081, v169
	v_mul_f32_e32 v1, 0x3b808081, v1
	v_mul_f32_e32 v172, 0x3b808081, v172
	v_mul_f32_e32 v173, 0x3b808081, v173
	v_mul_f32_e32 v176, 0x3b808081, v176
	v_mul_f32_e32 v166, 0x3b808081, v166
	v_mul_f32_e32 v167, 0x3b808081, v167
	v_mul_f32_e32 v168, v100, v168
	v_mul_f32_e32 v169, v105, v169
	v_mul_f32_e32 v1, v104, v1
	v_mul_f32_e32 v172, v101, v172
	v_mul_f32_e32 v173, v106, v173
	v_mul_f32_e32 v176, v102, v176
	v_mul_f32_e32 v177, v107, v166
	v_mul_f32_e32 v178, v103, v167
	v_cvt_pk_bf16_f32 v166, v1, v169
	v_cvt_pk_bf16_f32 v167, v173, v177
	v_cvt_pk_bf16_f32 v168, v168, v172
	v_cvt_pk_bf16_f32 v169, v176, v178
	global_store_dwordx4 v[170:171], v[166:169], off
	s_nop 0
	v_lshl_add_u64 v[172:173], v[158:159], 0, s[14:15]
	v_lshl_add_u64 v[168:169], s[6:7], 0, v[172:173]
	v_lshl_add_u64 v[174:175], v[168:169], 0, v[146:147]
	s_waitcnt vmcnt(15)
	v_mov_b32_e32 v166, v216
	v_mov_b32_e32 v167, v217
	v_max_u32_sdwa v168, v167, v165 dst_sel:DWORD dst_unused:UNUSED_PAD src0_sel:BYTE_0 src1_sel:DWORD
	v_max_u32_sdwa v169, v166, v165 dst_sel:DWORD dst_unused:UNUSED_PAD src0_sel:BYTE_1 src1_sel:DWORD
	v_max_u32_sdwa v1, v166, v165 dst_sel:DWORD dst_unused:UNUSED_PAD src0_sel:BYTE_0 src1_sel:DWORD
	v_max_u32_sdwa v176, v167, v165 dst_sel:DWORD dst_unused:UNUSED_PAD src0_sel:BYTE_1 src1_sel:DWORD
	v_max_u32_sdwa v177, v166, v165 dst_sel:DWORD dst_unused:UNUSED_PAD src0_sel:BYTE_2 src1_sel:DWORD
	v_max_u32_sdwa v178, v167, v165 dst_sel:DWORD dst_unused:UNUSED_PAD src0_sel:BYTE_2 src1_sel:DWORD
	v_max_u32_sdwa v166, v166, v165 dst_sel:DWORD dst_unused:UNUSED_PAD src0_sel:BYTE_3 src1_sel:DWORD
	v_max_u32_sdwa v167, v167, v165 dst_sel:DWORD dst_unused:UNUSED_PAD src0_sel:BYTE_3 src1_sel:DWORD
	v_cvt_f32_ubyte0_e32 v168, v168
	v_cvt_f32_ubyte0_e32 v169, v169
	v_cvt_f32_ubyte0_e32 v1, v1
	v_cvt_f32_ubyte0_e32 v176, v176
	v_cvt_f32_ubyte0_e32 v177, v177
	v_cvt_f32_ubyte0_e32 v178, v178
	v_cvt_f32_ubyte0_e32 v166, v166
	v_cvt_f32_ubyte0_e32 v167, v167
	v_mul_f32_e32 v168, 0x3b808081, v168
	v_mul_f32_e32 v169, 0x3b808081, v169
	v_mul_f32_e32 v1, 0x3b808081, v1
	v_mul_f32_e32 v176, 0x3b808081, v176
	v_mul_f32_e32 v177, 0x3b808081, v177
	v_mul_f32_e32 v178, 0x3b808081, v178
	v_mul_f32_e32 v166, 0x3b808081, v166
	v_mul_f32_e32 v167, 0x3b808081, v167
	v_mul_f32_e32 v168, v68, v168
	v_mul_f32_e32 v169, v73, v169
	v_mul_f32_e32 v1, v72, v1
	v_mul_f32_e32 v176, v69, v176
	v_mul_f32_e32 v177, v74, v177
	v_mul_f32_e32 v178, v70, v178
	v_mul_f32_e32 v179, v75, v166
	v_mul_f32_e32 v180, v71, v167
	v_cvt_pk_bf16_f32 v166, v1, v169
	v_cvt_pk_bf16_f32 v167, v177, v179
	v_cvt_pk_bf16_f32 v168, v168, v176
	v_cvt_pk_bf16_f32 v169, v178, v180
	global_store_dwordx4 v[170:171], v[166:169], off offset:256
	s_nop 0
	s_waitcnt vmcnt(15)
	v_mov_b32_e32 v166, v218
	v_mov_b32_e32 v167, v219
	v_max_u32_sdwa v1, v166, v165 dst_sel:DWORD dst_unused:UNUSED_PAD src0_sel:BYTE_0 src1_sel:DWORD
	v_lshl_add_u64 v[168:169], s[8:9], 0, v[172:173]
	v_lshl_add_u64 v[170:171], v[168:169], 0, v[156:157]
	v_max_u32_sdwa v168, v167, v165 dst_sel:DWORD dst_unused:UNUSED_PAD src0_sel:BYTE_0 src1_sel:DWORD
	v_max_u32_sdwa v169, v166, v165 dst_sel:DWORD dst_unused:UNUSED_PAD src0_sel:BYTE_1 src1_sel:DWORD
	v_max_u32_sdwa v172, v167, v165 dst_sel:DWORD dst_unused:UNUSED_PAD src0_sel:BYTE_1 src1_sel:DWORD
	v_max_u32_sdwa v173, v166, v165 dst_sel:DWORD dst_unused:UNUSED_PAD src0_sel:BYTE_2 src1_sel:DWORD
	v_max_u32_sdwa v176, v167, v165 dst_sel:DWORD dst_unused:UNUSED_PAD src0_sel:BYTE_2 src1_sel:DWORD
	v_max_u32_sdwa v166, v166, v165 dst_sel:DWORD dst_unused:UNUSED_PAD src0_sel:BYTE_3 src1_sel:DWORD
	v_max_u32_sdwa v167, v167, v165 dst_sel:DWORD dst_unused:UNUSED_PAD src0_sel:BYTE_3 src1_sel:DWORD
	v_cvt_f32_ubyte0_e32 v168, v168
	v_cvt_f32_ubyte0_e32 v169, v169
	v_cvt_f32_ubyte0_e32 v1, v1
	v_cvt_f32_ubyte0_e32 v172, v172
	v_cvt_f32_ubyte0_e32 v173, v173
	v_cvt_f32_ubyte0_e32 v176, v176
	v_cvt_f32_ubyte0_e32 v166, v166
	v_cvt_f32_ubyte0_e32 v167, v167
	v_mul_f32_e32 v168, 0x3b808081, v168
	v_mul_f32_e32 v169, 0x3b808081, v169
	v_mul_f32_e32 v1, 0x3b808081, v1
	v_mul_f32_e32 v172, 0x3b808081, v172
	v_mul_f32_e32 v173, 0x3b808081, v173
	v_mul_f32_e32 v176, 0x3b808081, v176
	v_mul_f32_e32 v166, 0x3b808081, v166
	v_mul_f32_e32 v167, 0x3b808081, v167
	v_mul_f32_e32 v168, v60, v168
	v_mul_f32_e32 v169, v65, v169
	v_mul_f32_e32 v1, v64, v1
	v_mul_f32_e32 v172, v61, v172
	v_mul_f32_e32 v173, v66, v173
	v_mul_f32_e32 v176, v62, v176
	v_mul_f32_e32 v177, v67, v166
	v_mul_f32_e32 v178, v63, v167
	v_cvt_pk_bf16_f32 v166, v1, v169
	v_cvt_pk_bf16_f32 v167, v173, v177
	v_cvt_pk_bf16_f32 v168, v168, v172
	v_cvt_pk_bf16_f32 v169, v176, v178
	global_store_dwordx4 v[170:171], v[166:169], off
	s_nop 0
	v_lshl_add_u64 v[172:173], v[158:159], 0, s[16:17]
	v_lshl_add_u64 v[168:169], s[6:7], 0, v[172:173]
	v_lshl_add_u64 v[174:175], v[168:169], 0, v[146:147]
	s_waitcnt vmcnt(15)
	v_mov_b32_e32 v166, v220
	v_mov_b32_e32 v167, v221
	v_max_u32_sdwa v168, v167, v165 dst_sel:DWORD dst_unused:UNUSED_PAD src0_sel:BYTE_0 src1_sel:DWORD
	v_max_u32_sdwa v169, v166, v165 dst_sel:DWORD dst_unused:UNUSED_PAD src0_sel:BYTE_1 src1_sel:DWORD
	v_max_u32_sdwa v1, v166, v165 dst_sel:DWORD dst_unused:UNUSED_PAD src0_sel:BYTE_0 src1_sel:DWORD
	v_max_u32_sdwa v176, v167, v165 dst_sel:DWORD dst_unused:UNUSED_PAD src0_sel:BYTE_1 src1_sel:DWORD
	v_max_u32_sdwa v177, v166, v165 dst_sel:DWORD dst_unused:UNUSED_PAD src0_sel:BYTE_2 src1_sel:DWORD
	v_max_u32_sdwa v178, v167, v165 dst_sel:DWORD dst_unused:UNUSED_PAD src0_sel:BYTE_2 src1_sel:DWORD
	v_max_u32_sdwa v166, v166, v165 dst_sel:DWORD dst_unused:UNUSED_PAD src0_sel:BYTE_3 src1_sel:DWORD
	v_max_u32_sdwa v167, v167, v165 dst_sel:DWORD dst_unused:UNUSED_PAD src0_sel:BYTE_3 src1_sel:DWORD
	v_cvt_f32_ubyte0_e32 v168, v168
	v_cvt_f32_ubyte0_e32 v169, v169
	v_cvt_f32_ubyte0_e32 v1, v1
	v_cvt_f32_ubyte0_e32 v176, v176
	v_cvt_f32_ubyte0_e32 v177, v177
	v_cvt_f32_ubyte0_e32 v178, v178
	v_cvt_f32_ubyte0_e32 v166, v166
	v_cvt_f32_ubyte0_e32 v167, v167
	v_mul_f32_e32 v168, 0x3b808081, v168
	v_mul_f32_e32 v169, 0x3b808081, v169
	v_mul_f32_e32 v1, 0x3b808081, v1
	v_mul_f32_e32 v176, 0x3b808081, v176
	v_mul_f32_e32 v177, 0x3b808081, v177
	v_mul_f32_e32 v178, 0x3b808081, v178
	v_mul_f32_e32 v166, 0x3b808081, v166
	v_mul_f32_e32 v167, 0x3b808081, v167
	v_mul_f32_e32 v168, v28, v168
	v_mul_f32_e32 v169, v33, v169
	v_mul_f32_e32 v1, v32, v1
	v_mul_f32_e32 v176, v29, v176
	v_mul_f32_e32 v177, v34, v177
	v_mul_f32_e32 v178, v30, v178
	v_mul_f32_e32 v179, v35, v166
	v_mul_f32_e32 v180, v31, v167
	v_cvt_pk_bf16_f32 v166, v1, v169
	v_cvt_pk_bf16_f32 v167, v177, v179
	v_cvt_pk_bf16_f32 v168, v168, v176
	v_cvt_pk_bf16_f32 v169, v178, v180
	global_store_dwordx4 v[170:171], v[166:169], off offset:256
	s_nop 0
	s_waitcnt vmcnt(15)
	v_mov_b32_e32 v166, v222
	v_mov_b32_e32 v167, v223
	v_max_u32_sdwa v1, v166, v165 dst_sel:DWORD dst_unused:UNUSED_PAD src0_sel:BYTE_0 src1_sel:DWORD
	v_lshl_add_u64 v[168:169], s[8:9], 0, v[172:173]
	v_lshl_add_u64 v[170:171], v[168:169], 0, v[156:157]
	v_max_u32_sdwa v168, v167, v165 dst_sel:DWORD dst_unused:UNUSED_PAD src0_sel:BYTE_0 src1_sel:DWORD
	v_max_u32_sdwa v169, v166, v165 dst_sel:DWORD dst_unused:UNUSED_PAD src0_sel:BYTE_1 src1_sel:DWORD
	v_max_u32_sdwa v172, v167, v165 dst_sel:DWORD dst_unused:UNUSED_PAD src0_sel:BYTE_1 src1_sel:DWORD
	v_max_u32_sdwa v173, v166, v165 dst_sel:DWORD dst_unused:UNUSED_PAD src0_sel:BYTE_2 src1_sel:DWORD
	v_max_u32_sdwa v176, v167, v165 dst_sel:DWORD dst_unused:UNUSED_PAD src0_sel:BYTE_2 src1_sel:DWORD
	v_max_u32_sdwa v166, v166, v165 dst_sel:DWORD dst_unused:UNUSED_PAD src0_sel:BYTE_3 src1_sel:DWORD
	v_max_u32_sdwa v167, v167, v165 dst_sel:DWORD dst_unused:UNUSED_PAD src0_sel:BYTE_3 src1_sel:DWORD
	v_cvt_f32_ubyte0_e32 v168, v168
	v_cvt_f32_ubyte0_e32 v169, v169
	v_cvt_f32_ubyte0_e32 v1, v1
	v_cvt_f32_ubyte0_e32 v172, v172
	v_cvt_f32_ubyte0_e32 v173, v173
	v_cvt_f32_ubyte0_e32 v176, v176
	v_cvt_f32_ubyte0_e32 v166, v166
	v_cvt_f32_ubyte0_e32 v167, v167
	v_mul_f32_e32 v168, 0x3b808081, v168
	v_mul_f32_e32 v169, 0x3b808081, v169
	v_mul_f32_e32 v1, 0x3b808081, v1
	v_mul_f32_e32 v172, 0x3b808081, v172
	v_mul_f32_e32 v173, 0x3b808081, v173
	v_mul_f32_e32 v176, 0x3b808081, v176
	v_mul_f32_e32 v166, 0x3b808081, v166
	v_mul_f32_e32 v167, 0x3b808081, v167
	v_mul_f32_e32 v168, v52, v168
	v_mul_f32_e32 v169, v57, v169
	v_mul_f32_e32 v1, v56, v1
	v_mul_f32_e32 v172, v53, v172
	v_mul_f32_e32 v173, v58, v173
	v_mul_f32_e32 v176, v54, v176
	v_mul_f32_e32 v177, v59, v166
	v_mul_f32_e32 v178, v55, v167
	v_cvt_pk_bf16_f32 v166, v1, v169
	v_cvt_pk_bf16_f32 v167, v173, v177
	v_cvt_pk_bf16_f32 v168, v168, v172
	v_cvt_pk_bf16_f32 v169, v176, v178
	global_store_dwordx4 v[170:171], v[166:169], off
	s_nop 0
	v_lshl_add_u64 v[172:173], v[158:159], 0, s[18:19]
	v_lshl_add_u64 v[168:169], s[6:7], 0, v[172:173]
	v_lshl_add_u64 v[174:175], v[168:169], 0, v[146:147]
	v_lshl_add_u64 v[158:159], v[158:159], 0, s[20:21]
	s_waitcnt vmcnt(15)
	v_mov_b32_e32 v166, v224
	v_mov_b32_e32 v167, v225
	v_max_u32_sdwa v168, v167, v165 dst_sel:DWORD dst_unused:UNUSED_PAD src0_sel:BYTE_0 src1_sel:DWORD
	v_max_u32_sdwa v169, v166, v165 dst_sel:DWORD dst_unused:UNUSED_PAD src0_sel:BYTE_1 src1_sel:DWORD
	v_max_u32_sdwa v1, v166, v165 dst_sel:DWORD dst_unused:UNUSED_PAD src0_sel:BYTE_0 src1_sel:DWORD
	v_max_u32_sdwa v176, v167, v165 dst_sel:DWORD dst_unused:UNUSED_PAD src0_sel:BYTE_1 src1_sel:DWORD
	v_max_u32_sdwa v177, v166, v165 dst_sel:DWORD dst_unused:UNUSED_PAD src0_sel:BYTE_2 src1_sel:DWORD
	v_max_u32_sdwa v178, v167, v165 dst_sel:DWORD dst_unused:UNUSED_PAD src0_sel:BYTE_2 src1_sel:DWORD
	v_max_u32_sdwa v166, v166, v165 dst_sel:DWORD dst_unused:UNUSED_PAD src0_sel:BYTE_3 src1_sel:DWORD
	v_max_u32_sdwa v167, v167, v165 dst_sel:DWORD dst_unused:UNUSED_PAD src0_sel:BYTE_3 src1_sel:DWORD
	v_cvt_f32_ubyte0_e32 v168, v168
	v_cvt_f32_ubyte0_e32 v169, v169
	v_cvt_f32_ubyte0_e32 v1, v1
	v_cvt_f32_ubyte0_e32 v176, v176
	v_cvt_f32_ubyte0_e32 v177, v177
	v_cvt_f32_ubyte0_e32 v178, v178
	v_cvt_f32_ubyte0_e32 v166, v166
	v_cvt_f32_ubyte0_e32 v167, v167
	v_mul_f32_e32 v168, 0x3b808081, v168
	v_mul_f32_e32 v169, 0x3b808081, v169
	v_mul_f32_e32 v1, 0x3b808081, v1
	v_mul_f32_e32 v176, 0x3b808081, v176
	v_mul_f32_e32 v177, 0x3b808081, v177
	v_mul_f32_e32 v178, 0x3b808081, v178
	v_mul_f32_e32 v166, 0x3b808081, v166
	v_mul_f32_e32 v167, 0x3b808081, v167
	v_mul_f32_e32 v168, v20, v168
	v_mul_f32_e32 v169, v25, v169
	v_mul_f32_e32 v1, v24, v1
	v_mul_f32_e32 v176, v21, v176
	v_mul_f32_e32 v177, v26, v177
	v_mul_f32_e32 v178, v22, v178
	v_mul_f32_e32 v179, v27, v166
	v_mul_f32_e32 v180, v23, v167
	v_cvt_pk_bf16_f32 v166, v1, v169
	v_cvt_pk_bf16_f32 v167, v177, v179
	v_cvt_pk_bf16_f32 v168, v168, v176
	v_cvt_pk_bf16_f32 v169, v178, v180
	global_store_dwordx4 v[170:171], v[166:169], off offset:256
	s_nop 0
	s_waitcnt vmcnt(15)
	v_mov_b32_e32 v166, v226
	v_mov_b32_e32 v167, v227
	v_max_u32_sdwa v1, v166, v165 dst_sel:DWORD dst_unused:UNUSED_PAD src0_sel:BYTE_0 src1_sel:DWORD
	v_lshl_add_u64 v[168:169], s[8:9], 0, v[172:173]
	v_lshl_add_u64 v[170:171], v[168:169], 0, v[156:157]
	v_max_u32_sdwa v168, v167, v165 dst_sel:DWORD dst_unused:UNUSED_PAD src0_sel:BYTE_0 src1_sel:DWORD
	v_max_u32_sdwa v169, v166, v165 dst_sel:DWORD dst_unused:UNUSED_PAD src0_sel:BYTE_1 src1_sel:DWORD
	v_max_u32_sdwa v172, v167, v165 dst_sel:DWORD dst_unused:UNUSED_PAD src0_sel:BYTE_1 src1_sel:DWORD
	v_max_u32_sdwa v173, v166, v165 dst_sel:DWORD dst_unused:UNUSED_PAD src0_sel:BYTE_2 src1_sel:DWORD
	v_max_u32_sdwa v176, v167, v165 dst_sel:DWORD dst_unused:UNUSED_PAD src0_sel:BYTE_2 src1_sel:DWORD
	v_max_u32_sdwa v166, v166, v165 dst_sel:DWORD dst_unused:UNUSED_PAD src0_sel:BYTE_3 src1_sel:DWORD
	v_max_u32_sdwa v167, v167, v165 dst_sel:DWORD dst_unused:UNUSED_PAD src0_sel:BYTE_3 src1_sel:DWORD
	v_cvt_f32_ubyte0_e32 v168, v168
	v_cvt_f32_ubyte0_e32 v169, v169
	v_cvt_f32_ubyte0_e32 v1, v1
	v_cvt_f32_ubyte0_e32 v172, v172
	v_cvt_f32_ubyte0_e32 v173, v173
	v_cvt_f32_ubyte0_e32 v176, v176
	v_cvt_f32_ubyte0_e32 v166, v166
	v_cvt_f32_ubyte0_e32 v167, v167
	v_mul_f32_e32 v168, 0x3b808081, v168
	v_mul_f32_e32 v169, 0x3b808081, v169
	v_mul_f32_e32 v1, 0x3b808081, v1
	v_mul_f32_e32 v172, 0x3b808081, v172
	v_mul_f32_e32 v173, 0x3b808081, v173
	v_mul_f32_e32 v176, 0x3b808081, v176
	v_mul_f32_e32 v166, 0x3b808081, v166
	v_mul_f32_e32 v167, 0x3b808081, v167
	v_mul_f32_e32 v168, v44, v168
	v_mul_f32_e32 v169, v49, v169
	v_mul_f32_e32 v1, v48, v1
	v_mul_f32_e32 v172, v45, v172
	v_mul_f32_e32 v173, v50, v173
	v_mul_f32_e32 v176, v46, v176
	v_mul_f32_e32 v177, v51, v166
	v_mul_f32_e32 v178, v47, v167
	v_cvt_pk_bf16_f32 v166, v1, v169
	v_cvt_pk_bf16_f32 v167, v173, v177
	v_cvt_pk_bf16_f32 v168, v168, v172
	v_cvt_pk_bf16_f32 v169, v176, v178
	global_store_dwordx4 v[170:171], v[166:169], off
	s_nop 0
	s_waitcnt vmcnt(15)
	v_mov_b32_e32 v166, v228
	v_mov_b32_e32 v167, v229
	v_max_u32_sdwa v1, v166, v165 dst_sel:DWORD dst_unused:UNUSED_PAD src0_sel:BYTE_0 src1_sel:DWORD
	v_lshl_add_u64 v[168:169], s[6:7], 0, v[158:159]
	v_lshl_add_u64 v[172:173], v[168:169], 0, v[146:147]
	v_max_u32_sdwa v168, v167, v165 dst_sel:DWORD dst_unused:UNUSED_PAD src0_sel:BYTE_0 src1_sel:DWORD
	v_max_u32_sdwa v169, v166, v165 dst_sel:DWORD dst_unused:UNUSED_PAD src0_sel:BYTE_1 src1_sel:DWORD
	v_max_u32_sdwa v174, v167, v165 dst_sel:DWORD dst_unused:UNUSED_PAD src0_sel:BYTE_1 src1_sel:DWORD
	v_max_u32_sdwa v175, v166, v165 dst_sel:DWORD dst_unused:UNUSED_PAD src0_sel:BYTE_2 src1_sel:DWORD
	v_max_u32_sdwa v176, v167, v165 dst_sel:DWORD dst_unused:UNUSED_PAD src0_sel:BYTE_2 src1_sel:DWORD
	v_max_u32_sdwa v166, v166, v165 dst_sel:DWORD dst_unused:UNUSED_PAD src0_sel:BYTE_3 src1_sel:DWORD
	v_max_u32_sdwa v167, v167, v165 dst_sel:DWORD dst_unused:UNUSED_PAD src0_sel:BYTE_3 src1_sel:DWORD
	v_cvt_f32_ubyte0_e32 v168, v168
	v_cvt_f32_ubyte0_e32 v169, v169
	v_cvt_f32_ubyte0_e32 v1, v1
	v_cvt_f32_ubyte0_e32 v174, v174
	v_cvt_f32_ubyte0_e32 v175, v175
	v_cvt_f32_ubyte0_e32 v176, v176
	v_cvt_f32_ubyte0_e32 v166, v166
	v_cvt_f32_ubyte0_e32 v167, v167
	v_mul_f32_e32 v168, 0x3b808081, v168
	v_mul_f32_e32 v169, 0x3b808081, v169
	v_mul_f32_e32 v1, 0x3b808081, v1
	v_mul_f32_e32 v174, 0x3b808081, v174
	v_mul_f32_e32 v175, 0x3b808081, v175
	v_mul_f32_e32 v176, 0x3b808081, v176
	v_mul_f32_e32 v166, 0x3b808081, v166
	v_mul_f32_e32 v167, 0x3b808081, v167
	v_mul_f32_e32 v168, v12, v168
	v_mul_f32_e32 v169, v17, v169
	v_mul_f32_e32 v1, v16, v1
	v_mul_f32_e32 v174, v13, v174
	v_mul_f32_e32 v175, v18, v175
	v_mul_f32_e32 v176, v14, v176
	v_mul_f32_e32 v177, v19, v166
	v_mul_f32_e32 v178, v15, v167
	v_cvt_pk_bf16_f32 v166, v1, v169
	v_cvt_pk_bf16_f32 v167, v175, v177
	v_cvt_pk_bf16_f32 v168, v168, v174
	v_cvt_pk_bf16_f32 v169, v176, v178
	global_store_dwordx4 v[170:171], v[166:169], off offset:256
	s_nop 0
	v_lshl_add_u64 v[158:159], s[8:9], 0, v[158:159]
	v_lshl_add_u64 v[168:169], v[158:159], 0, v[156:157]
	s_waitcnt vmcnt(15)
	v_mov_b32_e32 v166, v230
	v_mov_b32_e32 v167, v231
	v_max_u32_sdwa v156, v167, v165 dst_sel:DWORD dst_unused:UNUSED_PAD src0_sel:BYTE_0 src1_sel:DWORD
	v_max_u32_sdwa v157, v166, v165 dst_sel:DWORD dst_unused:UNUSED_PAD src0_sel:BYTE_1 src1_sel:DWORD
	v_max_u32_sdwa v158, v167, v165 dst_sel:DWORD dst_unused:UNUSED_PAD src0_sel:BYTE_1 src1_sel:DWORD
	v_max_u32_sdwa v159, v166, v165 dst_sel:DWORD dst_unused:UNUSED_PAD src0_sel:BYTE_2 src1_sel:DWORD
	v_max_u32_sdwa v170, v167, v165 dst_sel:DWORD dst_unused:UNUSED_PAD src0_sel:BYTE_2 src1_sel:DWORD
	v_max_u32_sdwa v1, v166, v165 dst_sel:DWORD dst_unused:UNUSED_PAD src0_sel:BYTE_0 src1_sel:DWORD
	v_max_u32_sdwa v166, v166, v165 dst_sel:DWORD dst_unused:UNUSED_PAD src0_sel:BYTE_3 src1_sel:DWORD
	v_max_u32_sdwa v167, v167, v165 dst_sel:DWORD dst_unused:UNUSED_PAD src0_sel:BYTE_3 src1_sel:DWORD
	v_cvt_f32_ubyte0_e32 v156, v156
	v_cvt_f32_ubyte0_e32 v157, v157
	v_cvt_f32_ubyte0_e32 v158, v158
	v_cvt_f32_ubyte0_e32 v159, v159
	v_cvt_f32_ubyte0_e32 v170, v170
	v_cvt_f32_ubyte0_e32 v1, v1
	v_cvt_f32_ubyte0_e32 v166, v166
	v_cvt_f32_ubyte0_e32 v167, v167
	v_mul_f32_e32 v156, 0x3b808081, v156
	v_mul_f32_e32 v157, 0x3b808081, v157
	v_mul_f32_e32 v158, 0x3b808081, v158
	v_mul_f32_e32 v159, 0x3b808081, v159
	v_mul_f32_e32 v170, 0x3b808081, v170
	v_mul_f32_e32 v1, 0x3b808081, v1
	v_mul_f32_e32 v166, 0x3b808081, v166
	v_mul_f32_e32 v167, 0x3b808081, v167
	v_mul_f32_e32 v171, v36, v156
	v_mul_f32_e32 v156, v41, v157
	v_mul_f32_e32 v158, v37, v158
	v_mul_f32_e32 v157, v42, v159
	v_mul_f32_e32 v159, v38, v170
	v_mul_f32_e32 v1, v40, v1
	v_mul_f32_e32 v166, v43, v166
	v_mul_f32_e32 v167, v39, v167
	v_cvt_pk_bf16_f32 v156, v1, v156
	v_cvt_pk_bf16_f32 v157, v157, v166
	v_cvt_pk_bf16_f32 v158, v171, v158
	v_cvt_pk_bf16_f32 v159, v159, v167
	global_store_dwordx4 v[168:169], v[156:159], off
	s_nop 0
	s_waitcnt vmcnt(15)
	v_mov_b32_e32 v156, v232
	v_mov_b32_e32 v157, v233
	v_max_u32_sdwa v1, v156, v165 dst_sel:DWORD dst_unused:UNUSED_PAD src0_sel:BYTE_0 src1_sel:DWORD
	v_max_u32_sdwa v158, v157, v165 dst_sel:DWORD dst_unused:UNUSED_PAD src0_sel:BYTE_0 src1_sel:DWORD
	v_max_u32_sdwa v159, v156, v165 dst_sel:DWORD dst_unused:UNUSED_PAD src0_sel:BYTE_1 src1_sel:DWORD
	v_max_u32_sdwa v166, v157, v165 dst_sel:DWORD dst_unused:UNUSED_PAD src0_sel:BYTE_1 src1_sel:DWORD
	v_max_u32_sdwa v167, v156, v165 dst_sel:DWORD dst_unused:UNUSED_PAD src0_sel:BYTE_2 src1_sel:DWORD
	v_max_u32_sdwa v170, v157, v165 dst_sel:DWORD dst_unused:UNUSED_PAD src0_sel:BYTE_2 src1_sel:DWORD
	v_max_u32_sdwa v156, v156, v165 dst_sel:DWORD dst_unused:UNUSED_PAD src0_sel:BYTE_3 src1_sel:DWORD
	v_max_u32_sdwa v157, v157, v165 dst_sel:DWORD dst_unused:UNUSED_PAD src0_sel:BYTE_3 src1_sel:DWORD
	v_cvt_f32_ubyte0_e32 v158, v158
	v_cvt_f32_ubyte0_e32 v159, v159
	v_cvt_f32_ubyte0_e32 v1, v1
	v_cvt_f32_ubyte0_e32 v166, v166
	v_cvt_f32_ubyte0_e32 v167, v167
	v_cvt_f32_ubyte0_e32 v170, v170
	v_cvt_f32_ubyte0_e32 v156, v156
	v_cvt_f32_ubyte0_e32 v157, v157
	v_mul_f32_e32 v158, 0x3b808081, v158
	v_mul_f32_e32 v159, 0x3b808081, v159
	v_mul_f32_e32 v1, 0x3b808081, v1
	v_mul_f32_e32 v166, 0x3b808081, v166
	v_mul_f32_e32 v167, 0x3b808081, v167
	v_mul_f32_e32 v170, 0x3b808081, v170
	v_mul_f32_e32 v156, 0x3b808081, v156
	v_mul_f32_e32 v157, 0x3b808081, v157
	v_mul_f32_e32 v158, v4, v158
	v_mul_f32_e32 v159, v9, v159
	v_mul_f32_e32 v1, v8, v1
	v_mul_f32_e32 v166, v5, v166
	v_mul_f32_e32 v167, v10, v167
	v_mul_f32_e32 v170, v6, v170
	v_mul_f32_e32 v171, v11, v156
	v_mul_f32_e32 v172, v7, v157
	v_cvt_pk_bf16_f32 v156, v1, v159
	v_cvt_pk_bf16_f32 v157, v167, v171
	v_cvt_pk_bf16_f32 v158, v158, v166
	v_cvt_pk_bf16_f32 v159, v170, v172
	global_store_dwordx4 v[168:169], v[156:159], off offset:256
	s_cbranch_execnz .LBB0_893

.LBB0_963:
	s_add_i32 s64, s64, s33
	s_cmpk_lt_i32 s64, 0x80
	s_barrier
	s_cbranch_scc0 .LBB0_1029

.LBB0_989:
	s_lshl_b32 s20, s11, 5
	s_lshl_b32 s29, s28, 8
	s_or_b32 s20, s29, s20
	v_or_b32_e32 v128, s20, v182
	s_lshl_b32 s20, s10, 8
	s_add_i32 s29, s20, s75
	v_or_b32_e32 v130, s29, v161
	v_ashrrev_i32_e32 v131, 31, v130
	v_lshlrev_b64 v[132:133], 11, v[130:131]
	v_ashrrev_i32_e32 v129, 31, v128
	v_lshl_add_u64 v[132:133], s[18:19], 0, v[132:133]
	v_lshlrev_b64 v[178:179], 1, v[128:129]
	v_lshl_add_u64 v[136:137], v[132:133], 0, v[178:179]
	s_barrier
	v_lshlrev_b32_e32 v241, 11, v130
	v_add_u32_e32 v241, v241, v178
	global_load_dwordx4 v[208:211], v241, s[18:19]
	global_load_dwordx4 v[212:215], v241, s[18:19] offset:256
	v_add_u32_e32 v242, 0x8000, v241
	global_load_dwordx4 v[216:219], v242, s[18:19]
	global_load_dwordx4 v[220:223], v242, s[18:19] offset:256
	v_add_u32_e32 v242, 0x10000, v241
	global_load_dwordx4 v[224:227], v242, s[18:19]
	global_load_dwordx4 v[228:231], v242, s[18:19] offset:256
	v_add_u32_e32 v242, 0x18000, v241
	global_load_dwordx4 v[232:235], v242, s[18:19]
	global_load_dwordx4 v[236:239], v242, s[18:19] offset:256
	s_nop 0
	v_or_b32_e32 v140, 16, v130
	v_ashrrev_i32_e32 v141, 31, v140
	v_lshlrev_b64 v[140:141], 11, v[140:141]
	v_lshl_add_u64 v[140:141], s[18:19], 0, v[140:141]
	v_lshl_add_u64 v[140:141], v[140:141], 0, v[178:179]
	v_xor_b32_e32 v131, 16, v192
	s_lshl_b32 s11, s11, 3
	s_add_i32 s11, s11, 0
	s_waitcnt vmcnt(6)
	v_mov_b32_e32 v132, v208
	v_mov_b32_e32 v133, v209
	v_mov_b32_e32 v134, v210
	v_mov_b32_e32 v135, v211
	v_mov_b32_e32 v136, v212
	v_mov_b32_e32 v137, v213
	v_mov_b32_e32 v138, v214
	v_mov_b32_e32 v139, v215
	v_add_u32_e32 v242, 0x40000, v241
	global_load_dwordx4 v[208:211], v242, s[18:19]
	global_load_dwordx4 v[212:215], v242, s[18:19] offset:256
	v_lshlrev_b32_e32 v142, 16, v132
	v_and_b32_e32 v143, 0xffff0000, v132
	v_lshlrev_b32_e32 v132, 16, v133
	v_and_b32_e32 v133, 0xffff0000, v133
	v_lshlrev_b32_e32 v144, 16, v134
	v_and_b32_e32 v145, 0xffff0000, v134
	v_lshlrev_b32_e32 v134, 16, v135
	v_and_b32_e32 v135, 0xffff0000, v135
	v_lshlrev_b32_e32 v146, 16, v136
	v_and_b32_e32 v147, 0xffff0000, v136
	v_lshlrev_b32_e32 v136, 16, v137
	v_and_b32_e32 v137, 0xffff0000, v137
	v_lshlrev_b32_e32 v148, 16, v138
	v_and_b32_e32 v149, 0xffff0000, v138
	v_lshlrev_b32_e32 v138, 16, v139
	v_and_b32_e32 v139, 0xffff0000, v139
	v_pk_fma_f32 v[102:103], v[132:133], s[26:27], v[102:103] op_sel_hi:[1,0,1]
	v_pk_fma_f32 v[100:101], v[142:143], s[26:27], v[100:101] op_sel_hi:[1,0,1]
	v_pk_fma_f32 v[98:99], v[134:135], s[26:27], v[98:99] op_sel_hi:[1,0,1]
	v_pk_fma_f32 v[96:97], v[144:145], s[26:27], v[96:97] op_sel_hi:[1,0,1]
	v_pk_fma_f32 v[90:91], v[136:137], s[26:27], v[90:91] op_sel_hi:[1,0,1]
	v_pk_fma_f32 v[88:89], v[146:147], s[26:27], v[88:89] op_sel_hi:[1,0,1]
	v_pk_fma_f32 v[82:83], v[138:139], s[26:27], v[82:83] op_sel_hi:[1,0,1]
	v_pk_fma_f32 v[80:81], v[148:149], s[26:27], v[80:81] op_sel_hi:[1,0,1]
	s_nop 0
	v_or_b32_e32 v140, 32, v130
	v_ashrrev_i32_e32 v141, 31, v140
	v_lshlrev_b64 v[140:141], 11, v[140:141]
	v_lshl_add_u64 v[140:141], s[18:19], 0, v[140:141]
	v_lshl_add_u64 v[140:141], v[140:141], 0, v[178:179]
	s_waitcnt vmcnt(7)
	v_mov_b32_e32 v132, v216
	v_mov_b32_e32 v133, v217
	v_mov_b32_e32 v134, v218
	v_mov_b32_e32 v135, v219
	v_lshlrev_b32_e32 v142, 16, v132
	v_and_b32_e32 v143, 0xffff0000, v132
	v_lshlrev_b32_e32 v132, 16, v133
	v_and_b32_e32 v133, 0xffff0000, v133
	v_lshlrev_b32_e32 v144, 16, v134
	v_and_b32_e32 v145, 0xffff0000, v134
	v_lshlrev_b32_e32 v134, 16, v135
	v_and_b32_e32 v135, 0xffff0000, v135
	s_waitcnt vmcnt(6)
	v_mov_b32_e32 v136, v220
	v_mov_b32_e32 v137, v221
	v_mov_b32_e32 v138, v222
	v_mov_b32_e32 v139, v223
	v_add_u32_e32 v242, 0x48000, v241
	global_load_dwordx4 v[216:219], v242, s[18:19]
	global_load_dwordx4 v[220:223], v242, s[18:19] offset:256
	v_lshlrev_b32_e32 v146, 16, v136
	v_and_b32_e32 v147, 0xffff0000, v136
	v_lshlrev_b32_e32 v136, 16, v137
	v_and_b32_e32 v137, 0xffff0000, v137
	v_lshlrev_b32_e32 v148, 16, v138
	v_and_b32_e32 v149, 0xffff0000, v138
	v_lshlrev_b32_e32 v138, 16, v139
	v_and_b32_e32 v139, 0xffff0000, v139
	v_pk_fma_f32 v[110:111], v[132:133], s[26:27], v[110:111] op_sel_hi:[1,0,1]
	v_pk_fma_f32 v[108:109], v[142:143], s[26:27], v[108:109] op_sel_hi:[1,0,1]
	v_pk_fma_f32 v[106:107], v[134:135], s[26:27], v[106:107] op_sel_hi:[1,0,1]
	v_pk_fma_f32 v[104:105], v[144:145], s[26:27], v[104:105] op_sel_hi:[1,0,1]
	v_pk_fma_f32 v[78:79], v[136:137], s[26:27], v[78:79] op_sel_hi:[1,0,1]
	v_pk_fma_f32 v[76:77], v[146:147], s[26:27], v[76:77] op_sel_hi:[1,0,1]
	v_pk_fma_f32 v[70:71], v[138:139], s[26:27], v[70:71] op_sel_hi:[1,0,1]
	v_pk_fma_f32 v[68:69], v[148:149], s[26:27], v[68:69] op_sel_hi:[1,0,1]
	s_nop 0
	v_or_b32_e32 v140, 48, v130
	v_ashrrev_i32_e32 v141, 31, v140
	v_lshlrev_b64 v[140:141], 11, v[140:141]
	v_lshl_add_u64 v[140:141], s[18:19], 0, v[140:141]
	v_lshl_add_u64 v[140:141], v[140:141], 0, v[178:179]
	s_waitcnt vmcnt(7)
	v_mov_b32_e32 v132, v224
	v_mov_b32_e32 v133, v225
	v_mov_b32_e32 v134, v226
	v_mov_b32_e32 v135, v227
	v_lshlrev_b32_e32 v142, 16, v132
	v_and_b32_e32 v143, 0xffff0000, v132
	v_lshlrev_b32_e32 v132, 16, v133
	v_and_b32_e32 v133, 0xffff0000, v133
	v_lshlrev_b32_e32 v144, 16, v134
	v_and_b32_e32 v145, 0xffff0000, v134
	v_lshlrev_b32_e32 v134, 16, v135
	v_and_b32_e32 v135, 0xffff0000, v135
	s_waitcnt vmcnt(6)
	v_mov_b32_e32 v136, v228
	v_mov_b32_e32 v137, v229
	v_mov_b32_e32 v138, v230
	v_mov_b32_e32 v139, v231
	v_add_u32_e32 v242, 0x50000, v241
	global_load_dwordx4 v[224:227], v242, s[18:19]
	global_load_dwordx4 v[228:231], v242, s[18:19] offset:256
	v_lshlrev_b32_e32 v146, 16, v136
	v_and_b32_e32 v147, 0xffff0000, v136
	v_lshlrev_b32_e32 v136, 16, v137
	v_and_b32_e32 v137, 0xffff0000, v137
	v_lshlrev_b32_e32 v148, 16, v138
	v_and_b32_e32 v149, 0xffff0000, v138
	v_lshlrev_b32_e32 v138, 16, v139
	v_and_b32_e32 v139, 0xffff0000, v139
	v_pk_fma_f32 v[122:123], v[132:133], s[26:27], v[122:123] op_sel_hi:[1,0,1]
	v_pk_fma_f32 v[120:121], v[142:143], s[26:27], v[120:121] op_sel_hi:[1,0,1]
	v_pk_fma_f32 v[114:115], v[134:135], s[26:27], v[114:115] op_sel_hi:[1,0,1]
	v_pk_fma_f32 v[112:113], v[144:145], s[26:27], v[112:113] op_sel_hi:[1,0,1]
	v_pk_fma_f32 v[94:95], v[136:137], s[26:27], v[94:95] op_sel_hi:[1,0,1]
	v_pk_fma_f32 v[92:93], v[146:147], s[26:27], v[92:93] op_sel_hi:[1,0,1]
	v_pk_fma_f32 v[86:87], v[138:139], s[26:27], v[86:87] op_sel_hi:[1,0,1]
	v_pk_fma_f32 v[84:85], v[148:149], s[26:27], v[84:85] op_sel_hi:[1,0,1]
	s_nop 0
	v_add_u32_e32 v140, 0x80, v130
	v_ashrrev_i32_e32 v141, 31, v140
	v_lshlrev_b64 v[140:141], 11, v[140:141]
	v_lshl_add_u64 v[140:141], s[18:19], 0, v[140:141]
	v_lshl_add_u64 v[140:141], v[140:141], 0, v[178:179]
	s_waitcnt vmcnt(7)
	v_mov_b32_e32 v132, v232
	v_mov_b32_e32 v133, v233
	v_mov_b32_e32 v134, v234
	v_mov_b32_e32 v135, v235
	v_lshlrev_b32_e32 v142, 16, v132
	v_and_b32_e32 v143, 0xffff0000, v132
	v_lshlrev_b32_e32 v132, 16, v133
	v_and_b32_e32 v133, 0xffff0000, v133
	v_lshlrev_b32_e32 v144, 16, v134
	v_and_b32_e32 v145, 0xffff0000, v134
	v_lshlrev_b32_e32 v134, 16, v135
	v_and_b32_e32 v135, 0xffff0000, v135
	s_waitcnt vmcnt(6)
	v_mov_b32_e32 v136, v236
	v_mov_b32_e32 v137, v237
	v_mov_b32_e32 v138, v238
	v_mov_b32_e32 v139, v239
	v_add_u32_e32 v242, 0x58000, v241
	global_load_dwordx4 v[232:235], v242, s[18:19]
	global_load_dwordx4 v[236:239], v242, s[18:19] offset:256
	v_lshlrev_b32_e32 v146, 16, v136
	v_and_b32_e32 v147, 0xffff0000, v136
	v_lshlrev_b32_e32 v136, 16, v137
	v_and_b32_e32 v137, 0xffff0000, v137
	v_lshlrev_b32_e32 v148, 16, v138
	v_and_b32_e32 v149, 0xffff0000, v138
	v_lshlrev_b32_e32 v138, 16, v139
	v_and_b32_e32 v139, 0xffff0000, v139
	v_pk_fma_f32 v[126:127], v[132:133], s[26:27], v[126:127] op_sel_hi:[1,0,1]
	v_pk_fma_f32 v[124:125], v[142:143], s[26:27], v[124:125] op_sel_hi:[1,0,1]
	v_pk_fma_f32 v[118:119], v[134:135], s[26:27], v[118:119] op_sel_hi:[1,0,1]
	v_pk_fma_f32 v[116:117], v[144:145], s[26:27], v[116:117] op_sel_hi:[1,0,1]
	v_pk_fma_f32 v[74:75], v[136:137], s[26:27], v[74:75] op_sel_hi:[1,0,1]
	v_pk_fma_f32 v[72:73], v[146:147], s[26:27], v[72:73] op_sel_hi:[1,0,1]
	v_pk_fma_f32 v[66:67], v[138:139], s[26:27], v[66:67] op_sel_hi:[1,0,1]
	v_pk_fma_f32 v[64:65], v[148:149], s[26:27], v[64:65] op_sel_hi:[1,0,1]
	s_nop 0
	v_add_u32_e32 v140, 0x90, v130
	v_ashrrev_i32_e32 v141, 31, v140
	v_lshlrev_b64 v[140:141], 11, v[140:141]
	v_lshl_add_u64 v[140:141], s[18:19], 0, v[140:141]
	v_lshl_add_u64 v[140:141], v[140:141], 0, v[178:179]
	s_waitcnt vmcnt(7)
	v_mov_b32_e32 v132, v208
	v_mov_b32_e32 v133, v209
	v_mov_b32_e32 v134, v210
	v_mov_b32_e32 v135, v211
	v_lshlrev_b32_e32 v142, 16, v132
	v_and_b32_e32 v143, 0xffff0000, v132
	v_lshlrev_b32_e32 v132, 16, v133
	v_and_b32_e32 v133, 0xffff0000, v133
	v_lshlrev_b32_e32 v144, 16, v134
	v_and_b32_e32 v145, 0xffff0000, v134
	v_lshlrev_b32_e32 v134, 16, v135
	v_and_b32_e32 v135, 0xffff0000, v135
	s_waitcnt vmcnt(6)
	v_mov_b32_e32 v136, v212
	v_mov_b32_e32 v137, v213
	v_mov_b32_e32 v138, v214
	v_mov_b32_e32 v139, v215
	v_lshlrev_b32_e32 v146, 16, v136
	v_and_b32_e32 v147, 0xffff0000, v136
	v_lshlrev_b32_e32 v136, 16, v137
	v_and_b32_e32 v137, 0xffff0000, v137
	v_lshlrev_b32_e32 v148, 16, v138
	v_and_b32_e32 v149, 0xffff0000, v138
	v_lshlrev_b32_e32 v138, 16, v139
	v_and_b32_e32 v139, 0xffff0000, v139
	v_pk_fma_f32 v[62:63], v[132:133], s[26:27], v[62:63] op_sel_hi:[1,0,1]
	v_pk_fma_f32 v[60:61], v[142:143], s[26:27], v[60:61] op_sel_hi:[1,0,1]
	v_pk_fma_f32 v[58:59], v[134:135], s[26:27], v[58:59] op_sel_hi:[1,0,1]
	v_pk_fma_f32 v[56:57], v[144:145], s[26:27], v[56:57] op_sel_hi:[1,0,1]
	v_pk_fma_f32 v[54:55], v[136:137], s[26:27], v[54:55] op_sel_hi:[1,0,1]
	v_pk_fma_f32 v[52:53], v[146:147], s[26:27], v[52:53] op_sel_hi:[1,0,1]
	v_pk_fma_f32 v[50:51], v[138:139], s[26:27], v[50:51] op_sel_hi:[1,0,1]
	v_pk_fma_f32 v[48:49], v[148:149], s[26:27], v[48:49] op_sel_hi:[1,0,1]
	s_nop 0
	v_add_u32_e32 v140, 0xa0, v130
	v_ashrrev_i32_e32 v141, 31, v140
	v_lshlrev_b64 v[140:141], 11, v[140:141]
	v_lshl_add_u64 v[140:141], s[18:19], 0, v[140:141]
	v_lshl_add_u64 v[140:141], v[140:141], 0, v[178:179]
	s_waitcnt vmcnt(5)
	v_mov_b32_e32 v132, v216
	v_mov_b32_e32 v133, v217
	v_mov_b32_e32 v134, v218
	v_mov_b32_e32 v135, v219
	v_lshlrev_b32_e32 v142, 16, v132
	v_and_b32_e32 v143, 0xffff0000, v132
	v_lshlrev_b32_e32 v132, 16, v133
	v_and_b32_e32 v133, 0xffff0000, v133
	v_lshlrev_b32_e32 v144, 16, v134
	v_and_b32_e32 v145, 0xffff0000, v134
	v_lshlrev_b32_e32 v134, 16, v135
	v_and_b32_e32 v135, 0xffff0000, v135
	s_waitcnt vmcnt(4)
	v_mov_b32_e32 v136, v220
	v_mov_b32_e32 v137, v221
	v_mov_b32_e32 v138, v222
	v_mov_b32_e32 v139, v223
	v_lshlrev_b32_e32 v146, 16, v136
	v_and_b32_e32 v147, 0xffff0000, v136
	v_lshlrev_b32_e32 v136, 16, v137
	v_and_b32_e32 v137, 0xffff0000, v137
	v_lshlrev_b32_e32 v148, 16, v138
	v_and_b32_e32 v149, 0xffff0000, v138
	v_lshlrev_b32_e32 v138, 16, v139
	v_and_b32_e32 v139, 0xffff0000, v139
	v_pk_fma_f32 v[46:47], v[132:133], s[26:27], v[46:47] op_sel_hi:[1,0,1]
	v_pk_fma_f32 v[44:45], v[142:143], s[26:27], v[44:45] op_sel_hi:[1,0,1]
	v_pk_fma_f32 v[42:43], v[134:135], s[26:27], v[42:43] op_sel_hi:[1,0,1]
	v_pk_fma_f32 v[40:41], v[144:145], s[26:27], v[40:41] op_sel_hi:[1,0,1]
	v_pk_fma_f32 v[38:39], v[136:137], s[26:27], v[38:39] op_sel_hi:[1,0,1]
	v_pk_fma_f32 v[36:37], v[146:147], s[26:27], v[36:37] op_sel_hi:[1,0,1]
	v_pk_fma_f32 v[34:35], v[138:139], s[26:27], v[34:35] op_sel_hi:[1,0,1]
	v_pk_fma_f32 v[32:33], v[148:149], s[26:27], v[32:33] op_sel_hi:[1,0,1]
	v_mov_b32_e32 v144, v101
	v_and_b32_e32 v140, 64, v192
	v_add_u32_e32 v154, 64, v140
	v_add_u32_e32 v140, 0xb0, v130
	v_ashrrev_i32_e32 v141, 31, v140
	v_lshlrev_b64 v[140:141], 11, v[140:141]
	v_lshl_add_u64 v[140:141], s[18:19], 0, v[140:141]
	v_lshl_add_u64 v[140:141], v[140:141], 0, v[178:179]
	v_cmp_lt_i32_e32 vcc, v131, v154
	v_mov_b32_e32 v145, v102
	v_mov_b32_e32 v146, v100
	v_mov_b32_e32 v147, v103
	v_cndmask_b32_e32 v131, v192, v131, vcc
	v_pk_add_f32 v[144:145], v[144:145], v[146:147]
	v_lshlrev_b32_e32 v130, 2, v131
	v_add_f32_e32 v131, v144, v145
	s_waitcnt vmcnt(3)
	v_mov_b32_e32 v132, v224
	v_mov_b32_e32 v133, v225
	v_mov_b32_e32 v134, v226
	v_mov_b32_e32 v135, v227
	v_lshlrev_b32_e32 v142, 16, v132
	v_and_b32_e32 v143, 0xffff0000, v132
	v_lshlrev_b32_e32 v132, 16, v133
	v_and_b32_e32 v133, 0xffff0000, v133
	v_lshlrev_b32_e32 v148, 16, v134
	v_and_b32_e32 v149, 0xffff0000, v134
	v_lshlrev_b32_e32 v134, 16, v135
	v_and_b32_e32 v135, 0xffff0000, v135
	s_waitcnt vmcnt(2)
	v_mov_b32_e32 v136, v228
	v_mov_b32_e32 v137, v229
	v_mov_b32_e32 v138, v230
	v_mov_b32_e32 v139, v231
	v_lshlrev_b32_e32 v150, 16, v136
	v_and_b32_e32 v151, 0xffff0000, v136
	v_lshlrev_b32_e32 v136, 16, v137
	v_and_b32_e32 v137, 0xffff0000, v137
	v_lshlrev_b32_e32 v152, 16, v138
	v_and_b32_e32 v153, 0xffff0000, v138
	v_lshlrev_b32_e32 v138, 16, v139
	v_and_b32_e32 v139, 0xffff0000, v139
	v_pk_fma_f32 v[30:31], v[132:133], s[26:27], v[30:31] op_sel_hi:[1,0,1]
	v_pk_fma_f32 v[28:29], v[142:143], s[26:27], v[28:29] op_sel_hi:[1,0,1]
	v_pk_fma_f32 v[26:27], v[134:135], s[26:27], v[26:27] op_sel_hi:[1,0,1]
	v_pk_fma_f32 v[24:25], v[148:149], s[26:27], v[24:25] op_sel_hi:[1,0,1]
	v_pk_fma_f32 v[22:23], v[136:137], s[26:27], v[22:23] op_sel_hi:[1,0,1]
	v_pk_fma_f32 v[20:21], v[150:151], s[26:27], v[20:21] op_sel_hi:[1,0,1]
	v_pk_fma_f32 v[18:19], v[138:139], s[26:27], v[18:19] op_sel_hi:[1,0,1]
	v_pk_fma_f32 v[16:17], v[152:153], s[26:27], v[16:17] op_sel_hi:[1,0,1]
	v_mov_b32_e32 v132, v97
	v_mov_b32_e32 v133, v98
	v_mov_b32_e32 v134, v96
	v_mov_b32_e32 v135, v99
	v_pk_add_f32 v[132:133], v[132:133], v[134:135]
	v_add_f32_e32 v149, v88, v89
	v_pk_add_f32 v[132:133], v[132:133], v[132:133] op_sel_hi:[0,1]
	v_add_f32_e32 v151, v90, v91
	v_mov_b32_e32 v148, v80
	v_mov_b32_e32 v150, v81
	v_mov_b32_e32 v152, v83
	v_add_f32_e32 v153, 0, v131
	v_mov_b32_e32 v132, v82
	v_pk_add_f32 v[134:135], v[148:149], v[150:151]
	v_pk_add_f32 v[132:133], v[132:133], v[152:153]
	v_xor_b32_e32 v131, 32, v192
	v_pk_add_f32 v[132:133], v[134:135], v[132:133]
	v_cmp_lt_i32_e32 vcc, v131, v154
	v_add_f32_e32 v132, v132, v133
	ds_bpermute_b32 v133, v130, v132
	v_cndmask_b32_e32 v131, v192, v131, vcc
	v_lshlrev_b32_e32 v131, 2, v131
	s_waitcnt lgkmcnt(0)
	v_add_f32_e32 v132, v132, v133
	ds_bpermute_b32 v133, v131, v132
	s_waitcnt lgkmcnt(0)
	v_add_f32_e32 v132, v132, v133
	v_fmamk_f32 v134, v132, 0xbc800000, v103
	v_fmamk_f32 v144, v132, 0xbc800000, v101
	v_fmamk_f32 v146, v132, 0xbc800000, v99
	v_fmamk_f32 v148, v132, 0xbc800000, v97
	v_fmamk_f32 v133, v132, 0xbc800000, v102
	v_fmamk_f32 v135, v132, 0xbc800000, v100
	v_fmamk_f32 v145, v132, 0xbc800000, v98
	v_fmamk_f32 v147, v132, 0xbc800000, v96
	v_fmamk_f32 v150, v132, 0xbc800000, v91
	v_fmamk_f32 v152, v132, 0xbc800000, v89
	v_mul_f32_e32 v144, v144, v144
	v_mul_f32_e32 v134, v134, v134
	v_mul_f32_e32 v148, v148, v148
	v_mul_f32_e32 v146, v146, v146
	v_fmamk_f32 v149, v132, 0xbc800000, v90
	v_fmamk_f32 v151, v132, 0xbc800000, v88
	v_fmamk_f32 v154, v132, 0xbc800000, v83
	v_fmamk_f32 v156, v132, 0xbc800000, v81
	v_mul_f32_e32 v152, v152, v152
	v_mul_f32_e32 v150, v150, v150
	v_fmac_f32_e32 v144, v135, v135
	v_fmac_f32_e32 v134, v133, v133
	v_fmac_f32_e32 v148, v147, v147
	v_fmac_f32_e32 v146, v145, v145
	v_fmamk_f32 v153, v132, 0xbc800000, v82
	v_fmamk_f32 v155, v132, 0xbc800000, v80
	v_mul_f32_e32 v156, v156, v156
	v_mul_f32_e32 v154, v154, v154
	v_fmac_f32_e32 v152, v151, v151
	v_fmac_f32_e32 v150, v149, v149
	v_add_f32_e32 v133, v144, v134
	v_add_f32_e32 v134, v148, v146
	v_fmac_f32_e32 v156, v155, v155
	v_fmac_f32_e32 v154, v153, v153
	v_add_f32_e32 v135, v152, v150
	v_add_f32_e32 v133, v133, v134
	v_add_f32_e32 v144, v156, v154
	v_add_f32_e32 v133, v135, v133
	v_add_f32_e32 v133, v144, v133
	ds_bpermute_b32 v134, v130, v133
	s_waitcnt lgkmcnt(0)
	v_add_f32_e32 v133, v133, v134
	ds_bpermute_b32 v134, v131, v133
	s_waitcnt vmcnt(1)
	v_mov_b32_e32 v136, v232
	v_mov_b32_e32 v137, v233
	v_mov_b32_e32 v138, v234
	v_mov_b32_e32 v139, v235
	v_lshlrev_b32_e32 v144, 16, v136
	v_and_b32_e32 v145, 0xffff0000, v136
	v_lshlrev_b32_e32 v136, 16, v137
	v_and_b32_e32 v137, 0xffff0000, v137
	v_lshlrev_b32_e32 v146, 16, v138
	v_and_b32_e32 v147, 0xffff0000, v138
	v_lshlrev_b32_e32 v138, 16, v139
	v_and_b32_e32 v139, 0xffff0000, v139
	s_waitcnt vmcnt(0)
	v_mov_b32_e32 v140, v236
	v_mov_b32_e32 v141, v237
	v_mov_b32_e32 v142, v238
	v_mov_b32_e32 v143, v239
	v_lshlrev_b32_e32 v148, 16, v140
	v_and_b32_e32 v149, 0xffff0000, v140
	v_lshlrev_b32_e32 v140, 16, v141
	v_and_b32_e32 v141, 0xffff0000, v141
	v_lshlrev_b32_e32 v150, 16, v142
	v_and_b32_e32 v151, 0xffff0000, v142
	v_lshlrev_b32_e32 v142, 16, v143
	v_and_b32_e32 v143, 0xffff0000, v143
	v_pk_fma_f32 v[14:15], v[136:137], s[26:27], v[14:15] op_sel_hi:[1,0,1]
	v_pk_fma_f32 v[12:13], v[144:145], s[26:27], v[12:13] op_sel_hi:[1,0,1]
	v_pk_fma_f32 v[10:11], v[138:139], s[26:27], v[10:11] op_sel_hi:[1,0,1]
	v_pk_fma_f32 v[8:9], v[146:147], s[26:27], v[8:9] op_sel_hi:[1,0,1]
	v_pk_fma_f32 v[6:7], v[140:141], s[26:27], v[6:7] op_sel_hi:[1,0,1]
	v_pk_fma_f32 v[4:5], v[148:149], s[26:27], v[4:5] op_sel_hi:[1,0,1]
	v_pk_fma_f32 v[2:3], v[142:143], s[26:27], v[2:3] op_sel_hi:[1,0,1]
	v_pk_fma_f32 v[0:1], v[150:151], s[26:27], v[0:1] op_sel_hi:[1,0,1]
	s_nop 0
	s_and_saveexec_b64 s[30:31], s[0:1]
	s_cbranch_execz .LBB0_991
	s_lshl_b32 s29, s66, 11
	s_add_i32 s29, s11, s29
	v_mul_f32_e32 v132, 0x3c800000, v132
	v_add_u32_e32 v135, s29, v184
	s_waitcnt lgkmcnt(0)
	v_add_f32_e32 v133, v133, v134
	ds_write_b64 v135, v[132:133]

.LBB0_1255:
	s_add_i32 s56, s56, s25
	s_cmpk_lt_i32 s56, 0x80
	s_barrier
	s_cbranch_scc0 .LBB0_1324

.LBB0_1284:
	s_lshl_b32 s8, s60, 5
	s_lshl_b32 s9, s26, 8
	s_or_b32 s8, s9, s8
	s_lshl_b32 s18, s58, 8
	v_or_b32_e32 v128, s8, v180
	s_add_i32 s8, s18, s70
	v_or_b32_e32 v130, s8, v181
	v_ashrrev_i32_e32 v131, 31, v130
	v_lshlrev_b64 v[132:133], 11, v[130:131]
	v_ashrrev_i32_e32 v129, 31, v128
	v_lshl_add_u64 v[134:135], s[16:17], 0, v[132:133]
	v_lshlrev_b64 v[132:133], 1, v[128:129]
	v_lshl_add_u64 v[138:139], v[134:135], 0, v[132:133]
	s_barrier
	v_lshlrev_b32_e32 v241, 11, v130
	v_add_u32_e32 v241, v241, v132
	global_load_dwordx4 v[208:211], v241, s[16:17]
	global_load_dwordx4 v[212:215], v241, s[16:17] offset:256
	v_add_u32_e32 v242, 0x8000, v241
	global_load_dwordx4 v[216:219], v242, s[16:17]
	global_load_dwordx4 v[220:223], v242, s[16:17] offset:256
	v_add_u32_e32 v242, 0x10000, v241
	global_load_dwordx4 v[224:227], v242, s[16:17]
	global_load_dwordx4 v[228:231], v242, s[16:17] offset:256
	v_add_u32_e32 v242, 0x18000, v241
	global_load_dwordx4 v[232:235], v242, s[16:17]
	global_load_dwordx4 v[236:239], v242, s[16:17] offset:256
	s_nop 0
	v_or_b32_e32 v142, 16, v130
	v_ashrrev_i32_e32 v143, 31, v142
	v_lshlrev_b64 v[142:143], 11, v[142:143]
	v_lshl_add_u64 v[142:143], s[16:17], 0, v[142:143]
	v_lshl_add_u64 v[142:143], v[142:143], 0, v[132:133]
	v_xor_b32_e32 v131, 16, v191
	s_lshl_b32 s8, s60, 3
	s_add_i32 s28, s8, 0
	s_waitcnt vmcnt(6)
	v_mov_b32_e32 v134, v208
	v_mov_b32_e32 v135, v209
	v_mov_b32_e32 v136, v210
	v_mov_b32_e32 v137, v211
	v_mov_b32_e32 v138, v212
	v_mov_b32_e32 v139, v213
	v_mov_b32_e32 v140, v214
	v_mov_b32_e32 v141, v215
	v_add_u32_e32 v242, 0x40000, v241
	global_load_dwordx4 v[208:211], v242, s[16:17]
	global_load_dwordx4 v[212:215], v242, s[16:17] offset:256
	v_lshlrev_b32_e32 v144, 16, v134
	v_and_b32_e32 v145, 0xffff0000, v134
	v_lshlrev_b32_e32 v134, 16, v135
	v_and_b32_e32 v135, 0xffff0000, v135
	v_lshlrev_b32_e32 v146, 16, v136
	v_and_b32_e32 v147, 0xffff0000, v136
	v_lshlrev_b32_e32 v136, 16, v137
	v_and_b32_e32 v137, 0xffff0000, v137
	v_lshlrev_b32_e32 v148, 16, v138
	v_and_b32_e32 v149, 0xffff0000, v138
	v_lshlrev_b32_e32 v138, 16, v139
	v_and_b32_e32 v139, 0xffff0000, v139
	v_lshlrev_b32_e32 v150, 16, v140
	v_and_b32_e32 v151, 0xffff0000, v140
	v_lshlrev_b32_e32 v140, 16, v141
	v_and_b32_e32 v141, 0xffff0000, v141
	v_pk_fma_f32 v[82:83], v[134:135], s[24:25], v[82:83] op_sel_hi:[1,0,1]
	v_pk_fma_f32 v[80:81], v[144:145], s[24:25], v[80:81] op_sel_hi:[1,0,1]
	v_pk_fma_f32 v[78:79], v[136:137], s[24:25], v[78:79] op_sel_hi:[1,0,1]
	v_pk_fma_f32 v[76:77], v[146:147], s[24:25], v[76:77] op_sel_hi:[1,0,1]
	v_pk_fma_f32 v[74:75], v[138:139], s[24:25], v[74:75] op_sel_hi:[1,0,1]
	v_pk_fma_f32 v[72:73], v[148:149], s[24:25], v[72:73] op_sel_hi:[1,0,1]
	v_pk_fma_f32 v[66:67], v[140:141], s[24:25], v[66:67] op_sel_hi:[1,0,1]
	v_pk_fma_f32 v[64:65], v[150:151], s[24:25], v[64:65] op_sel_hi:[1,0,1]
	s_nop 0
	v_or_b32_e32 v142, 32, v130
	v_ashrrev_i32_e32 v143, 31, v142
	v_lshlrev_b64 v[142:143], 11, v[142:143]
	v_lshl_add_u64 v[142:143], s[16:17], 0, v[142:143]
	v_lshl_add_u64 v[142:143], v[142:143], 0, v[132:133]
	s_waitcnt vmcnt(7)
	v_mov_b32_e32 v134, v216
	v_mov_b32_e32 v135, v217
	v_mov_b32_e32 v136, v218
	v_mov_b32_e32 v137, v219
	v_lshlrev_b32_e32 v144, 16, v134
	v_and_b32_e32 v145, 0xffff0000, v134
	v_lshlrev_b32_e32 v134, 16, v135
	v_and_b32_e32 v135, 0xffff0000, v135
	v_lshlrev_b32_e32 v146, 16, v136
	v_and_b32_e32 v147, 0xffff0000, v136
	v_lshlrev_b32_e32 v136, 16, v137
	v_and_b32_e32 v137, 0xffff0000, v137
	s_waitcnt vmcnt(6)
	v_mov_b32_e32 v138, v220
	v_mov_b32_e32 v139, v221
	v_mov_b32_e32 v140, v222
	v_mov_b32_e32 v141, v223
	v_add_u32_e32 v242, 0x48000, v241
	global_load_dwordx4 v[216:219], v242, s[16:17]
	global_load_dwordx4 v[220:223], v242, s[16:17] offset:256
	v_lshlrev_b32_e32 v148, 16, v138
	v_and_b32_e32 v149, 0xffff0000, v138
	v_lshlrev_b32_e32 v138, 16, v139
	v_and_b32_e32 v139, 0xffff0000, v139
	v_lshlrev_b32_e32 v150, 16, v140
	v_and_b32_e32 v151, 0xffff0000, v140
	v_lshlrev_b32_e32 v140, 16, v141
	v_and_b32_e32 v141, 0xffff0000, v141
	v_pk_fma_f32 v[126:127], v[134:135], s[24:25], v[126:127] op_sel_hi:[1,0,1]
	v_pk_fma_f32 v[124:125], v[144:145], s[24:25], v[124:125] op_sel_hi:[1,0,1]
	v_pk_fma_f32 v[106:107], v[136:137], s[24:25], v[106:107] op_sel_hi:[1,0,1]
	v_pk_fma_f32 v[104:105], v[146:147], s[24:25], v[104:105] op_sel_hi:[1,0,1]
	v_pk_fma_f32 v[94:95], v[138:139], s[24:25], v[94:95] op_sel_hi:[1,0,1]
	v_pk_fma_f32 v[92:93], v[148:149], s[24:25], v[92:93] op_sel_hi:[1,0,1]
	v_pk_fma_f32 v[90:91], v[140:141], s[24:25], v[90:91] op_sel_hi:[1,0,1]
	v_pk_fma_f32 v[88:89], v[150:151], s[24:25], v[88:89] op_sel_hi:[1,0,1]
	s_nop 0
	v_or_b32_e32 v142, 48, v130
	v_ashrrev_i32_e32 v143, 31, v142
	v_lshlrev_b64 v[142:143], 11, v[142:143]
	v_lshl_add_u64 v[142:143], s[16:17], 0, v[142:143]
	v_lshl_add_u64 v[142:143], v[142:143], 0, v[132:133]
	s_waitcnt vmcnt(7)
	v_mov_b32_e32 v134, v224
	v_mov_b32_e32 v135, v225
	v_mov_b32_e32 v136, v226
	v_mov_b32_e32 v137, v227
	v_lshlrev_b32_e32 v144, 16, v134
	v_and_b32_e32 v145, 0xffff0000, v134
	v_lshlrev_b32_e32 v134, 16, v135
	v_and_b32_e32 v135, 0xffff0000, v135
	v_lshlrev_b32_e32 v146, 16, v136
	v_and_b32_e32 v147, 0xffff0000, v136
	v_lshlrev_b32_e32 v136, 16, v137
	v_and_b32_e32 v137, 0xffff0000, v137
	s_waitcnt vmcnt(6)
	v_mov_b32_e32 v138, v228
	v_mov_b32_e32 v139, v229
	v_mov_b32_e32 v140, v230
	v_mov_b32_e32 v141, v231
	v_add_u32_e32 v242, 0x50000, v241
	global_load_dwordx4 v[224:227], v242, s[16:17]
	global_load_dwordx4 v[228:231], v242, s[16:17] offset:256
	v_lshlrev_b32_e32 v148, 16, v138
	v_and_b32_e32 v149, 0xffff0000, v138
	v_lshlrev_b32_e32 v138, 16, v139
	v_and_b32_e32 v139, 0xffff0000, v139
	v_lshlrev_b32_e32 v150, 16, v140
	v_and_b32_e32 v151, 0xffff0000, v140
	v_lshlrev_b32_e32 v140, 16, v141
	v_and_b32_e32 v141, 0xffff0000, v141
	v_pk_fma_f32 v[118:119], v[134:135], s[24:25], v[118:119] op_sel_hi:[1,0,1]
	v_pk_fma_f32 v[116:117], v[144:145], s[24:25], v[116:117] op_sel_hi:[1,0,1]
	v_pk_fma_f32 v[110:111], v[136:137], s[24:25], v[110:111] op_sel_hi:[1,0,1]
	v_pk_fma_f32 v[108:109], v[146:147], s[24:25], v[108:109] op_sel_hi:[1,0,1]
	v_pk_fma_f32 v[102:103], v[138:139], s[24:25], v[102:103] op_sel_hi:[1,0,1]
	v_pk_fma_f32 v[100:101], v[148:149], s[24:25], v[100:101] op_sel_hi:[1,0,1]
	v_pk_fma_f32 v[98:99], v[140:141], s[24:25], v[98:99] op_sel_hi:[1,0,1]
	v_pk_fma_f32 v[96:97], v[150:151], s[24:25], v[96:97] op_sel_hi:[1,0,1]
	s_nop 0
	v_add_u32_e32 v142, 0x80, v130
	v_ashrrev_i32_e32 v143, 31, v142
	v_lshlrev_b64 v[142:143], 11, v[142:143]
	v_lshl_add_u64 v[142:143], s[16:17], 0, v[142:143]
	v_lshl_add_u64 v[142:143], v[142:143], 0, v[132:133]
	s_waitcnt vmcnt(7)
	v_mov_b32_e32 v134, v232
	v_mov_b32_e32 v135, v233
	v_mov_b32_e32 v136, v234
	v_mov_b32_e32 v137, v235
	v_lshlrev_b32_e32 v144, 16, v134
	v_and_b32_e32 v145, 0xffff0000, v134
	v_lshlrev_b32_e32 v134, 16, v135
	v_and_b32_e32 v135, 0xffff0000, v135
	v_lshlrev_b32_e32 v146, 16, v136
	v_and_b32_e32 v147, 0xffff0000, v136
	v_lshlrev_b32_e32 v136, 16, v137
	v_and_b32_e32 v137, 0xffff0000, v137
	s_waitcnt vmcnt(6)
	v_mov_b32_e32 v138, v236
	v_mov_b32_e32 v139, v237
	v_mov_b32_e32 v140, v238
	v_mov_b32_e32 v141, v239
	v_add_u32_e32 v242, 0x58000, v241
	global_load_dwordx4 v[232:235], v242, s[16:17]
	global_load_dwordx4 v[236:239], v242, s[16:17] offset:256
	v_lshlrev_b32_e32 v148, 16, v138
	v_and_b32_e32 v149, 0xffff0000, v138
	v_lshlrev_b32_e32 v138, 16, v139
	v_and_b32_e32 v139, 0xffff0000, v139
	v_lshlrev_b32_e32 v150, 16, v140
	v_and_b32_e32 v151, 0xffff0000, v140
	v_lshlrev_b32_e32 v140, 16, v141
	v_and_b32_e32 v141, 0xffff0000, v141
	v_pk_fma_f32 v[122:123], v[134:135], s[24:25], v[122:123] op_sel_hi:[1,0,1]
	v_pk_fma_f32 v[120:121], v[144:145], s[24:25], v[120:121] op_sel_hi:[1,0,1]
	v_pk_fma_f32 v[114:115], v[136:137], s[24:25], v[114:115] op_sel_hi:[1,0,1]
	v_pk_fma_f32 v[112:113], v[146:147], s[24:25], v[112:113] op_sel_hi:[1,0,1]
	v_pk_fma_f32 v[86:87], v[138:139], s[24:25], v[86:87] op_sel_hi:[1,0,1]
	v_pk_fma_f32 v[84:85], v[148:149], s[24:25], v[84:85] op_sel_hi:[1,0,1]
	v_pk_fma_f32 v[70:71], v[140:141], s[24:25], v[70:71] op_sel_hi:[1,0,1]
	v_pk_fma_f32 v[68:69], v[150:151], s[24:25], v[68:69] op_sel_hi:[1,0,1]
	s_nop 0
	v_add_u32_e32 v142, 0x90, v130
	v_ashrrev_i32_e32 v143, 31, v142
	v_lshlrev_b64 v[142:143], 11, v[142:143]
	v_lshl_add_u64 v[142:143], s[16:17], 0, v[142:143]
	v_lshl_add_u64 v[142:143], v[142:143], 0, v[132:133]
	s_waitcnt vmcnt(7)
	v_mov_b32_e32 v134, v208
	v_mov_b32_e32 v135, v209
	v_mov_b32_e32 v136, v210
	v_mov_b32_e32 v137, v211
	v_lshlrev_b32_e32 v144, 16, v134
	v_and_b32_e32 v145, 0xffff0000, v134
	v_lshlrev_b32_e32 v134, 16, v135
	v_and_b32_e32 v135, 0xffff0000, v135
	v_lshlrev_b32_e32 v146, 16, v136
	v_and_b32_e32 v147, 0xffff0000, v136
	v_lshlrev_b32_e32 v136, 16, v137
	v_and_b32_e32 v137, 0xffff0000, v137
	s_waitcnt vmcnt(6)
	v_mov_b32_e32 v138, v212
	v_mov_b32_e32 v139, v213
	v_mov_b32_e32 v140, v214
	v_mov_b32_e32 v141, v215
	v_lshlrev_b32_e32 v148, 16, v138
	v_and_b32_e32 v149, 0xffff0000, v138
	v_lshlrev_b32_e32 v138, 16, v139
	v_and_b32_e32 v139, 0xffff0000, v139
	v_lshlrev_b32_e32 v150, 16, v140
	v_and_b32_e32 v151, 0xffff0000, v140
	v_lshlrev_b32_e32 v140, 16, v141
	v_and_b32_e32 v141, 0xffff0000, v141
	v_pk_fma_f32 v[62:63], v[134:135], s[24:25], v[62:63] op_sel_hi:[1,0,1]
	v_pk_fma_f32 v[60:61], v[144:145], s[24:25], v[60:61] op_sel_hi:[1,0,1]
	v_pk_fma_f32 v[58:59], v[136:137], s[24:25], v[58:59] op_sel_hi:[1,0,1]
	v_pk_fma_f32 v[56:57], v[146:147], s[24:25], v[56:57] op_sel_hi:[1,0,1]
	v_pk_fma_f32 v[54:55], v[138:139], s[24:25], v[54:55] op_sel_hi:[1,0,1]
	v_pk_fma_f32 v[52:53], v[148:149], s[24:25], v[52:53] op_sel_hi:[1,0,1]
	v_pk_fma_f32 v[50:51], v[140:141], s[24:25], v[50:51] op_sel_hi:[1,0,1]
	v_pk_fma_f32 v[48:49], v[150:151], s[24:25], v[48:49] op_sel_hi:[1,0,1]
	s_nop 0
	v_add_u32_e32 v142, 0xa0, v130
	v_ashrrev_i32_e32 v143, 31, v142
	v_lshlrev_b64 v[142:143], 11, v[142:143]
	v_lshl_add_u64 v[142:143], s[16:17], 0, v[142:143]
	v_lshl_add_u64 v[142:143], v[142:143], 0, v[132:133]
	s_waitcnt vmcnt(5)
	v_mov_b32_e32 v134, v216
	v_mov_b32_e32 v135, v217
	v_mov_b32_e32 v136, v218
	v_mov_b32_e32 v137, v219
	v_lshlrev_b32_e32 v144, 16, v134
	v_and_b32_e32 v145, 0xffff0000, v134
	v_lshlrev_b32_e32 v134, 16, v135
	v_and_b32_e32 v135, 0xffff0000, v135
	v_lshlrev_b32_e32 v146, 16, v136
	v_and_b32_e32 v147, 0xffff0000, v136
	v_lshlrev_b32_e32 v136, 16, v137
	v_and_b32_e32 v137, 0xffff0000, v137
	s_waitcnt vmcnt(4)
	v_mov_b32_e32 v138, v220
	v_mov_b32_e32 v139, v221
	v_mov_b32_e32 v140, v222
	v_mov_b32_e32 v141, v223
	v_lshlrev_b32_e32 v148, 16, v138
	v_and_b32_e32 v149, 0xffff0000, v138
	v_lshlrev_b32_e32 v138, 16, v139
	v_and_b32_e32 v139, 0xffff0000, v139
	v_lshlrev_b32_e32 v150, 16, v140
	v_and_b32_e32 v151, 0xffff0000, v140
	v_lshlrev_b32_e32 v140, 16, v141
	v_and_b32_e32 v141, 0xffff0000, v141
	v_pk_fma_f32 v[46:47], v[134:135], s[24:25], v[46:47] op_sel_hi:[1,0,1]
	v_pk_fma_f32 v[44:45], v[144:145], s[24:25], v[44:45] op_sel_hi:[1,0,1]
	v_pk_fma_f32 v[42:43], v[136:137], s[24:25], v[42:43] op_sel_hi:[1,0,1]
	v_pk_fma_f32 v[40:41], v[146:147], s[24:25], v[40:41] op_sel_hi:[1,0,1]
	v_pk_fma_f32 v[38:39], v[138:139], s[24:25], v[38:39] op_sel_hi:[1,0,1]
	v_pk_fma_f32 v[36:37], v[148:149], s[24:25], v[36:37] op_sel_hi:[1,0,1]
	v_pk_fma_f32 v[34:35], v[140:141], s[24:25], v[34:35] op_sel_hi:[1,0,1]
	v_pk_fma_f32 v[32:33], v[150:151], s[24:25], v[32:33] op_sel_hi:[1,0,1]
	v_mov_b32_e32 v144, v81
	v_and_b32_e32 v142, 64, v191
	v_add_u32_e32 v154, 64, v142
	v_add_u32_e32 v142, 0xb0, v130
	v_ashrrev_i32_e32 v143, 31, v142
	v_lshlrev_b64 v[142:143], 11, v[142:143]
	v_lshl_add_u64 v[142:143], s[16:17], 0, v[142:143]
	v_lshl_add_u64 v[132:133], v[142:143], 0, v[132:133]
	v_cmp_lt_i32_e32 vcc, v131, v154
	v_mov_b32_e32 v145, v82
	v_mov_b32_e32 v146, v80
	v_mov_b32_e32 v147, v83
	v_cndmask_b32_e32 v131, v191, v131, vcc
	v_pk_add_f32 v[144:145], v[144:145], v[146:147]
	v_lshlrev_b32_e32 v130, 2, v131
	v_add_f32_e32 v131, v144, v145
	s_waitcnt vmcnt(3)
	v_mov_b32_e32 v134, v224
	v_mov_b32_e32 v135, v225
	v_mov_b32_e32 v136, v226
	v_mov_b32_e32 v137, v227
	v_lshlrev_b32_e32 v142, 16, v134
	v_and_b32_e32 v143, 0xffff0000, v134
	v_lshlrev_b32_e32 v134, 16, v135
	v_and_b32_e32 v135, 0xffff0000, v135
	v_lshlrev_b32_e32 v148, 16, v136
	v_and_b32_e32 v149, 0xffff0000, v136
	v_lshlrev_b32_e32 v136, 16, v137
	v_and_b32_e32 v137, 0xffff0000, v137
	s_waitcnt vmcnt(2)
	v_mov_b32_e32 v138, v228
	v_mov_b32_e32 v139, v229
	v_mov_b32_e32 v140, v230
	v_mov_b32_e32 v141, v231
	v_lshlrev_b32_e32 v150, 16, v138
	v_and_b32_e32 v151, 0xffff0000, v138
	v_lshlrev_b32_e32 v138, 16, v139
	v_and_b32_e32 v139, 0xffff0000, v139
	v_lshlrev_b32_e32 v152, 16, v140
	v_and_b32_e32 v153, 0xffff0000, v140
	v_lshlrev_b32_e32 v140, 16, v141
	v_and_b32_e32 v141, 0xffff0000, v141
	v_pk_fma_f32 v[30:31], v[134:135], s[24:25], v[30:31] op_sel_hi:[1,0,1]
	v_pk_fma_f32 v[28:29], v[142:143], s[24:25], v[28:29] op_sel_hi:[1,0,1]
	v_pk_fma_f32 v[26:27], v[136:137], s[24:25], v[26:27] op_sel_hi:[1,0,1]
	v_pk_fma_f32 v[24:25], v[148:149], s[24:25], v[24:25] op_sel_hi:[1,0,1]
	v_pk_fma_f32 v[22:23], v[138:139], s[24:25], v[22:23] op_sel_hi:[1,0,1]
	v_pk_fma_f32 v[20:21], v[150:151], s[24:25], v[20:21] op_sel_hi:[1,0,1]
	v_pk_fma_f32 v[18:19], v[140:141], s[24:25], v[18:19] op_sel_hi:[1,0,1]
	v_pk_fma_f32 v[16:17], v[152:153], s[24:25], v[16:17] op_sel_hi:[1,0,1]
	v_mov_b32_e32 v134, v77
	v_mov_b32_e32 v135, v78
	v_mov_b32_e32 v148, v76
	v_mov_b32_e32 v149, v79
	v_pk_add_f32 v[134:135], v[134:135], v[148:149]
	v_add_f32_e32 v151, v72, v73
	v_pk_add_f32 v[134:135], v[134:135], v[134:135] op_sel_hi:[0,1]
	v_add_f32_e32 v153, v74, v75
	v_mov_b32_e32 v150, v64
	v_mov_b32_e32 v152, v65
	v_mov_b32_e32 v132, v67
	v_add_f32_e32 v133, 0, v131
	v_mov_b32_e32 v134, v66
	v_pk_add_f32 v[146:147], v[150:151], v[152:153]
	v_pk_add_f32 v[132:133], v[134:135], v[132:133]
	v_xor_b32_e32 v131, 32, v191
	v_pk_add_f32 v[132:133], v[146:147], v[132:133]
	v_cmp_lt_i32_e32 vcc, v131, v154
	v_add_f32_e32 v132, v132, v133
	ds_bpermute_b32 v133, v130, v132
	v_cndmask_b32_e32 v131, v191, v131, vcc
	v_lshlrev_b32_e32 v131, 2, v131
	s_waitcnt lgkmcnt(0)
	v_add_f32_e32 v132, v132, v133
	ds_bpermute_b32 v133, v131, v132
	s_waitcnt lgkmcnt(0)
	v_add_f32_e32 v132, v132, v133
	v_fmamk_f32 v134, v132, 0xbc800000, v83
	v_fmamk_f32 v144, v132, 0xbc800000, v81
	v_fmamk_f32 v146, v132, 0xbc800000, v79
	v_fmamk_f32 v148, v132, 0xbc800000, v77
	v_fmamk_f32 v133, v132, 0xbc800000, v82
	v_fmamk_f32 v135, v132, 0xbc800000, v80
	v_fmamk_f32 v145, v132, 0xbc800000, v78
	v_fmamk_f32 v147, v132, 0xbc800000, v76
	v_fmamk_f32 v150, v132, 0xbc800000, v75
	v_fmamk_f32 v152, v132, 0xbc800000, v73
	v_mul_f32_e32 v144, v144, v144
	v_mul_f32_e32 v134, v134, v134
	v_mul_f32_e32 v148, v148, v148
	v_mul_f32_e32 v146, v146, v146
	v_fmamk_f32 v149, v132, 0xbc800000, v74
	v_fmamk_f32 v151, v132, 0xbc800000, v72
	v_fmamk_f32 v154, v132, 0xbc800000, v67
	v_fmamk_f32 v156, v132, 0xbc800000, v65
	v_mul_f32_e32 v152, v152, v152
	v_mul_f32_e32 v150, v150, v150
	v_fmac_f32_e32 v144, v135, v135
	v_fmac_f32_e32 v134, v133, v133
	v_fmac_f32_e32 v148, v147, v147
	v_fmac_f32_e32 v146, v145, v145
	v_fmamk_f32 v153, v132, 0xbc800000, v66
	v_fmamk_f32 v155, v132, 0xbc800000, v64
	v_mul_f32_e32 v156, v156, v156
	v_mul_f32_e32 v154, v154, v154
	v_fmac_f32_e32 v152, v151, v151
	v_fmac_f32_e32 v150, v149, v149
	v_add_f32_e32 v133, v144, v134
	v_add_f32_e32 v134, v148, v146
	v_fmac_f32_e32 v156, v155, v155
	v_fmac_f32_e32 v154, v153, v153
	v_add_f32_e32 v135, v152, v150
	v_add_f32_e32 v133, v133, v134
	v_add_f32_e32 v144, v156, v154
	v_add_f32_e32 v133, v135, v133
	v_add_f32_e32 v133, v144, v133
	ds_bpermute_b32 v134, v130, v133
	s_waitcnt lgkmcnt(0)
	v_add_f32_e32 v133, v133, v134
	ds_bpermute_b32 v134, v131, v133
	s_waitcnt vmcnt(1)
	v_mov_b32_e32 v136, v232
	v_mov_b32_e32 v137, v233
	v_mov_b32_e32 v138, v234
	v_mov_b32_e32 v139, v235
	v_lshlrev_b32_e32 v144, 16, v136
	v_and_b32_e32 v145, 0xffff0000, v136
	v_lshlrev_b32_e32 v136, 16, v137
	v_and_b32_e32 v137, 0xffff0000, v137
	v_lshlrev_b32_e32 v146, 16, v138
	v_and_b32_e32 v147, 0xffff0000, v138
	v_lshlrev_b32_e32 v138, 16, v139
	v_and_b32_e32 v139, 0xffff0000, v139
	s_waitcnt vmcnt(0)
	v_mov_b32_e32 v140, v236
	v_mov_b32_e32 v141, v237
	v_mov_b32_e32 v142, v238
	v_mov_b32_e32 v143, v239
	v_lshlrev_b32_e32 v148, 16, v140
	v_and_b32_e32 v149, 0xffff0000, v140
	v_lshlrev_b32_e32 v140, 16, v141
	v_and_b32_e32 v141, 0xffff0000, v141
	v_lshlrev_b32_e32 v150, 16, v142
	v_and_b32_e32 v151, 0xffff0000, v142
	v_lshlrev_b32_e32 v142, 16, v143
	v_and_b32_e32 v143, 0xffff0000, v143
	v_pk_fma_f32 v[14:15], v[136:137], s[24:25], v[14:15] op_sel_hi:[1,0,1]
	v_pk_fma_f32 v[12:13], v[144:145], s[24:25], v[12:13] op_sel_hi:[1,0,1]
	v_pk_fma_f32 v[10:11], v[138:139], s[24:25], v[10:11] op_sel_hi:[1,0,1]
	v_pk_fma_f32 v[8:9], v[146:147], s[24:25], v[8:9] op_sel_hi:[1,0,1]
	v_pk_fma_f32 v[6:7], v[140:141], s[24:25], v[6:7] op_sel_hi:[1,0,1]
	v_pk_fma_f32 v[4:5], v[148:149], s[24:25], v[4:5] op_sel_hi:[1,0,1]
	v_pk_fma_f32 v[2:3], v[142:143], s[24:25], v[2:3] op_sel_hi:[1,0,1]
	v_pk_fma_f32 v[0:1], v[150:151], s[24:25], v[0:1] op_sel_hi:[1,0,1]
	s_nop 0
	s_and_saveexec_b64 s[8:9], s[0:1]
	s_cbranch_execz .LBB0_1286
	s_lshl_b32 s29, s59, 11
	s_add_i32 s29, s28, s29
	v_mul_f32_e32 v132, 0x3c800000, v132
	v_add_u32_e32 v135, s29, v183
	s_waitcnt lgkmcnt(0)
	v_add_f32_e32 v133, v133, v134
	ds_write_b64 v135, v[132:133]

	.amdhsa_kernel _Z6mk_fwd4Args
		.amdhsa_group_segment_fixed_size 0
		.amdhsa_private_segment_fixed_size 0
		.amdhsa_kernarg_size 472
		.amdhsa_user_sgpr_count 2
		.amdhsa_user_sgpr_dispatch_ptr 0
		.amdhsa_user_sgpr_queue_ptr 0
		.amdhsa_user_sgpr_kernarg_segment_ptr 1
		.amdhsa_user_sgpr_dispatch_id 0
		.amdhsa_user_sgpr_kernarg_preload_length 0
		.amdhsa_user_sgpr_kernarg_preload_offset 0
		.amdhsa_user_sgpr_private_segment_size 0
		.amdhsa_uses_dynamic_stack 0
		.amdhsa_enable_private_segment 0
		.amdhsa_system_sgpr_workgroup_id_x 1
		.amdhsa_system_sgpr_workgroup_id_y 0
		.amdhsa_system_sgpr_workgroup_id_z 0
		.amdhsa_system_sgpr_workgroup_info 0
		.amdhsa_system_vgpr_workitem_id 2
		.amdhsa_next_free_vgpr 248
		.amdhsa_next_free_sgpr 98
		.amdhsa_accum_offset 248
		.amdhsa_reserve_vcc 1
		.amdhsa_float_round_mode_32 0
		.amdhsa_float_round_mode_16_64 0
		.amdhsa_float_denorm_mode_32 3
		.amdhsa_float_denorm_mode_16_64 3
		.amdhsa_dx10_clamp 1
		.amdhsa_ieee_mode 1
		.amdhsa_fp16_overflow 0
		.amdhsa_tg_split 0
		.amdhsa_exception_fp_ieee_invalid_op 0
		.amdhsa_exception_fp_denorm_src 0
		.amdhsa_exception_fp_ieee_div_zero 0
		.amdhsa_exception_fp_ieee_overflow 0
		.amdhsa_exception_fp_ieee_underflow 0
		.amdhsa_exception_fp_ieee_inexact 0
		.amdhsa_exception_int_div_zero 0
	.end_amdhsa_kernel

amdhsa.kernels:
  - .agpr_count:     0
    .args:
      - .offset:         0
        .size:           216
        .value_kind:     by_value
      - .offset:         216
        .size:           4
        .value_kind:     hidden_block_count_x
      - .offset:         220
        .size:           4
        .value_kind:     hidden_block_count_y
      - .offset:         224
        .size:           4
        .value_kind:     hidden_block_count_z
      - .offset:         228
        .size:           2
        .value_kind:     hidden_group_size_x
      - .offset:         230
        .size:           2
        .value_kind:     hidden_group_size_y
      - .offset:         232
        .size:           2
        .value_kind:     hidden_group_size_z
      - .offset:         234
        .size:           2
        .value_kind:     hidden_remainder_x
      - .offset:         236
        .size:           2
        .value_kind:     hidden_remainder_y
      - .offset:         238
        .size:           2
        .value_kind:     hidden_remainder_z
      - .offset:         256
        .size:           8
        .value_kind:     hidden_global_offset_x
      - .offset:         264
        .size:           8
        .value_kind:     hidden_global_offset_y
      - .offset:         272
        .size:           8
        .value_kind:     hidden_global_offset_z
      - .offset:         280
        .size:           2
        .value_kind:     hidden_grid_dims
      - .offset:         304
        .size:           8
        .value_kind:     hidden_multigrid_sync_arg
      - .offset:         336
        .size:           4
        .value_kind:     hidden_dynamic_lds_size
    .group_segment_fixed_size: 0
    .kernarg_segment_align: 8
    .kernarg_segment_size: 472
    .language:       OpenCL C
    .language_version:
      - 2
      - 0
    .max_flat_workgroup_size: 512
    .name:           _Z6mk_fwd4Args
    .private_segment_fixed_size: 0
    .sgpr_count:     104
    .sgpr_spill_count: 71
    .symbol:         _Z6mk_fwd4Args.kd
    .uniform_work_group_size: 1
    .uses_dynamic_stack: false
    .vgpr_count:     248
    .vgpr_spill_count: 0
    .wavefront_size: 64
